# k13 plus non-temporal hint on P5 streaming input loads
# baseline (speedup 1.0000x reference)
; #define lane lane_id()
; __device__ __forceinline__ float silu(float x) { return x / (1.f + __expf(-x)); }
; __global__ void __launch_bounds__(NWAVES * 64, 2) hybrid_fwd(Args args) {
;     ...
;             const v4u* p1 = (const v4u*)(O1 + (size_t)m * 2048) + lane; const v4u* p2 = (const v4u*)(O2 + (size_t)m * 2048) + lane;
;             const v4u* pg = (const v4u*)(GD + (size_t)m * 2048) + lane;
;             const v4u* pb = (const v4u*)(OB + (size_t)m * 2048) + lane; const v4u* pm = (const v4u*)(GM + (size_t)m * 2048) + lane;
;             v4u a[4], b[4], gt[4], ab[4], gm[4];
; #pragma unroll
;             for (int j = 0; j < 4; ++j) { a[j] = p1[64 * j]; b[j] = p2[64 * j]; gt[j] = pg[64 * j]; ab[j] = pb[64 * j]; gm[j] = pm[64 * j]; }
;             v4u* po = (v4u*)(MIX + (size_t)m * 4096) + lane;
; #pragma unroll
;             for (int j = 0; j < 4; ++j) { float d[8]; float ss = 0.f;
; #pragma unroll
;                 for (int e = 0; e < 4; ++e) { const float d0 = bflo(a[j][e]) - lam * bflo(b[j][e]), d1 = bfhi(a[j][e]) - lam * bfhi(b[j][e]); d[2 * e] = d0; d[2 * e + 1] = d1; ss += d0 * d0 + d1 * d1; }
;                 ss += __shfl_xor(ss, 1); ss += __shfl_xor(ss, 2); ss += __shfl_xor(ss, 4); ss += __shfl_xor(ss, 8); ss += __shfl_xor(ss, 16);
.LBB0_847:
	s_add_u32 s2, s28, s16
	v_mbcnt_lo_u32_b32 v6, -1, 0
	v_mbcnt_hi_u32_b32 v6, -1, v6
	s_addc_u32 s3, s29, s17
	v_mbcnt_lo_u32_b32 v8, -1, 0
	v_mbcnt_hi_u32_b32 v8, -1, v8
	v_mbcnt_lo_u32_b32 v10, -1, 0
	v_mbcnt_hi_u32_b32 v10, -1, v10
	v_ashrrev_i32_e32 v7, 31, v6
	v_ashrrev_i32_e32 v9, 31, v8
	v_lshl_add_u64 v[8:9], v[8:9], 4, s[2:3]
	v_ashrrev_i32_e32 v11, 31, v10
	v_add_co_u32_e32 v8, vcc, s0, v8
	v_lshl_add_u64 v[10:11], v[10:11], 4, s[2:3]
	s_nop 0
	v_addc_co_u32_e32 v9, vcc, 0, v9, vcc
	v_add_co_u32_e32 v10, vcc, s1, v10
	v_lshl_add_u64 v[6:7], v[6:7], 4, s[2:3]
	s_nop 0
	v_addc_co_u32_e32 v11, vcc, 0, v11, vcc
	v_mbcnt_lo_u32_b32 v12, -1, 0
	v_mbcnt_hi_u32_b32 v12, -1, v12
	v_mbcnt_lo_u32_b32 v14, -1, 0
	v_mbcnt_hi_u32_b32 v14, -1, v14
	global_load_dwordx4 v[78:81], v[6:7], off nt
	global_load_dwordx4 v[96:99], v[8:9], off nt
	global_load_dwordx4 v[74:77], v[10:11], off nt
	v_ashrrev_i32_e32 v13, 31, v12
	v_lshl_add_u64 v[12:13], v[12:13], 4, s[2:3]
	v_add_co_u32_e32 v12, vcc, s11, v12
	v_ashrrev_i32_e32 v15, 31, v14
	s_nop 0
	v_addc_co_u32_e32 v13, vcc, 0, v13, vcc
	global_load_dwordx4 v[66:69], v[12:13], off nt
	v_lshl_add_u64 v[14:15], v[14:15], 4, s[2:3]
	v_add_co_u32_e32 v86, vcc, s20, v14
	s_add_u32 s2, s28, s6
	s_nop 0
	v_addc_co_u32_e32 v87, vcc, 0, v15, vcc
	global_load_dwordx4 v[70:73], v[86:87], off nt
	global_load_dwordx4 v[58:61], v[6:7], off offset:1024 nt
	global_load_dwordx4 v[62:65], v[8:9], off offset:1024 nt
	global_load_dwordx4 v[54:57], v[10:11], off offset:1024 nt
	global_load_dwordx4 v[46:49], v[12:13], off offset:1024 nt
	global_load_dwordx4 v[50:53], v[86:87], off offset:1024 nt
	global_load_dwordx4 v[38:41], v[6:7], off offset:2048 nt
	global_load_dwordx4 v[42:45], v[8:9], off offset:2048 nt
	global_load_dwordx4 v[34:37], v[10:11], off offset:2048 nt
	global_load_dwordx4 v[26:29], v[12:13], off offset:2048 nt
	global_load_dwordx4 v[30:33], v[86:87], off offset:2048 nt
	global_load_dwordx4 v[18:21], v[6:7], off offset:3072 nt
	global_load_dwordx4 v[22:25], v[8:9], off offset:3072 nt
	global_load_dwordx4 v[14:17], v[10:11], off offset:3072 nt
	s_nop 0
	global_load_dwordx4 v[6:9], v[12:13], off offset:3072 nt
	s_nop 0
	global_load_dwordx4 v[10:13], v[86:87], off offset:3072 nt
	v_mbcnt_lo_u32_b32 v86, -1, 0
	v_mbcnt_hi_u32_b32 v86, -1, v86
	s_addc_u32 s3, s29, s7
	v_ashrrev_i32_e32 v87, 31, v86
	v_lshl_add_u64 v[86:87], v[86:87], 4, s[2:3]
	s_add_i32 s27, s27, s68
	s_add_u32 s6, s6, s8
	s_addc_u32 s7, s7, s9
	s_add_u32 s16, s16, s18
	s_addc_u32 s17, s17, s19
	s_cmpk_lt_i32 s27, 0x4000
	s_waitcnt vmcnt(19)
	v_lshlrev_b32_e32 v105, 16, v79
	s_waitcnt vmcnt(18)
	v_lshlrev_b32_e32 v100, 16, v96
	v_lshlrev_b32_e32 v101, 16, v97
	v_lshlrev_b32_e32 v104, 16, v78
	s_waitcnt vmcnt(17)
	v_lshlrev_b32_e32 v95, 16, v75
	v_lshlrev_b32_e32 v106, 16, v74
	v_pk_fma_f32 v[100:101], v[2:3], v[100:101], v[104:105] neg_lo:[1,0,0] neg_hi:[1,0,0]
	v_mul_f32_e32 v104, 0xbfb8aa3b, v106
	v_and_b32_e32 v107, 0xffff0000, v75
	v_mul_f32_e32 v75, 0xbfb8aa3b, v95
	v_exp_f32_e32 v104, v104
	v_exp_f32_e32 v105, v75
	v_and_b32_e32 v108, 0xffff0000, v74
	v_mul_f32_e32 v74, 0xbfb8aa3b, v108
	v_exp_f32_e32 v74, v74
	v_pk_add_f32 v[104:105], v[104:105], 1.0 op_sel_hi:[1,0]
	v_and_b32_e32 v96, 0xffff0000, v96
	v_div_scale_f32 v75, s[2:3], v105, v105, v95
	v_rcp_f32_e32 v109, v75
	v_and_b32_e32 v97, 0xffff0000, v97
	v_and_b32_e32 v79, 0xffff0000, v79
	v_and_b32_e32 v78, 0xffff0000, v78
	v_fma_f32 v110, -v75, v109, 1.0
	v_fmac_f32_e32 v109, v110, v109
	v_div_scale_f32 v110, vcc, v95, v105, v95
	v_mul_f32_e32 v111, v110, v109
	v_fma_f32 v112, -v75, v111, v110
	v_fmac_f32_e32 v111, v112, v109
	v_fma_f32 v75, -v75, v111, v110
	v_div_fmas_f32 v75, v75, v109, v111
	v_div_fixup_f32 v105, v75, v105, v95
	v_div_scale_f32 v75, s[2:3], v104, v104, v106
	v_rcp_f32_e32 v95, v75
	v_lshlrev_b32_e32 v102, 16, v98
	v_and_b32_e32 v98, 0xffff0000, v98
	v_lshlrev_b32_e32 v103, 16, v99
	v_fma_f32 v109, -v75, v95, 1.0
	v_fmac_f32_e32 v95, v109, v95
	v_div_scale_f32 v109, vcc, v106, v104, v106
	v_mul_f32_e32 v110, v109, v95
	v_fma_f32 v111, -v75, v110, v109
	v_fmac_f32_e32 v110, v111, v95
	v_fma_f32 v75, -v75, v110, v109
	v_div_fmas_f32 v75, v75, v95, v110
	v_div_fixup_f32 v104, v75, v104, v106
	v_mul_f32_e32 v75, 0xbfb8aa3b, v107
	v_exp_f32_e32 v75, v75
	v_and_b32_e32 v99, 0xffff0000, v99
	v_pk_fma_f32 v[78:79], v[2:3], v[96:97], v[78:79] neg_lo:[1,0,0] neg_hi:[1,0,0]
	v_pk_add_f32 v[74:75], v[74:75], 1.0 op_sel_hi:[1,0]
	s_nop 0
	v_div_scale_f32 v95, s[2:3], v75, v75, v107
	v_rcp_f32_e32 v106, v95
	v_pk_mul_f32 v[96:97], v[78:79], v[78:79]
	v_fma_f32 v109, -v95, v106, 1.0
	v_fmac_f32_e32 v106, v109, v106
	v_div_scale_f32 v109, vcc, v107, v75, v107
	v_mul_f32_e32 v110, v109, v106
	v_fma_f32 v111, -v95, v110, v109
	v_fmac_f32_e32 v110, v111, v106
	v_fma_f32 v95, -v95, v110, v109
	v_div_fmas_f32 v95, v95, v106, v110
	v_div_fixup_f32 v75, v95, v75, v107
	v_div_scale_f32 v95, s[2:3], v74, v74, v108
	v_rcp_f32_e32 v106, v95
	v_pk_fma_f32 v[96:97], v[100:101], v[100:101], v[96:97]
	v_fma_f32 v107, -v95, v106, 1.0
	v_fmac_f32_e32 v106, v107, v106
	v_div_scale_f32 v107, vcc, v108, v74, v108
	v_mul_f32_e32 v109, v107, v106
	v_fma_f32 v110, -v95, v109, v107
	v_fmac_f32_e32 v109, v110, v106
	v_fma_f32 v95, -v95, v109, v107
	v_div_fmas_f32 v95, v95, v106, v109
	v_lshlrev_b32_e32 v107, 16, v81
	v_lshlrev_b32_e32 v106, 16, v80
	v_and_b32_e32 v81, 0xffff0000, v81
	v_and_b32_e32 v80, 0xffff0000, v80
	v_pk_fma_f32 v[80:81], v[2:3], v[98:99], v[80:81] neg_lo:[1,0,0] neg_hi:[1,0,0]
	v_pk_fma_f32 v[102:103], v[2:3], v[102:103], v[106:107] neg_lo:[1,0,0] neg_hi:[1,0,0]
	v_pk_mul_f32 v[98:99], v[80:81], v[80:81]
	v_div_fixup_f32 v74, v95, v74, v108
	v_pk_fma_f32 v[98:99], v[102:103], v[102:103], v[98:99]
	v_add_f32_e32 v95, v96, v97
	v_add_f32_e32 v95, v95, v98
	v_add_f32_e32 v95, v95, v99
	ds_bpermute_b32 v96, v88, v95
	s_waitcnt lgkmcnt(0)
; __device__ __forceinline__ unsigned pk2(float lo, float hi) { return f2bf(lo) | (f2bf(hi) << 16); }
; __device__ __forceinline__ float silu(float x) { return x / (1.f + __expf(-x)); }
; __global__ void __launch_bounds__(NWAVES * 64, 2) hybrid_fwd(Args args) {
;     ...
;                 ss += __shfl_xor(ss, 1); ss += __shfl_xor(ss, 2); ss += __shfl_xor(ss, 4); ss += __shfl_xor(ss, 8); ss += __shfl_xor(ss, 16);
;                 const float rstd = (1.f - LAMBDA_INIT) / sqrtf(ss * (1.f / 256.f) + RMS_EPS); v4u o;
; #pragma unroll
;                 for (int e = 0; e < 4; ++e) { const f32x4 s4 = (e >> 1) ? sl1 : sl0;
;                     o[e] = pk2(d[2 * e] * rstd * s4[(e & 1) * 2] * silu(bflo(gt[j][e])), d[2 * e + 1] * rstd * s4[(e & 1) * 2 + 1] * silu(bfhi(gt[j][e]))); }
;                 po[64 * j] = o;
	v_add_f32_e32 v95, v95, v96
	ds_bpermute_b32 v96, v89, v95
	s_waitcnt lgkmcnt(0)
	v_add_f32_e32 v95, v95, v96
	ds_bpermute_b32 v96, v90, v95
	s_waitcnt lgkmcnt(0)
	v_add_f32_e32 v95, v95, v96
	ds_bpermute_b32 v96, v91, v95
	s_waitcnt lgkmcnt(0)
	v_add_f32_e32 v95, v95, v96
	ds_bpermute_b32 v96, v92, v95
	s_waitcnt lgkmcnt(0)
	v_add_f32_e32 v95, v95, v96
	v_fmamk_f32 v95, v95, 0x3b800000, v93
	v_cmp_gt_f32_e32 vcc, s22, v95
	v_mul_f32_e32 v96, 0x4f800000, v95
	s_nop 0
	v_cndmask_b32_e32 v95, v95, v96, vcc
	v_sqrt_f32_e32 v96, v95
	s_nop 0
	v_add_u32_e32 v97, -1, v96
	v_fma_f32 v98, -v97, v96, v95
	v_cmp_ge_f32_e64 s[2:3], 0, v98
	v_add_u32_e32 v98, 1, v96
	s_nop 0
	v_cndmask_b32_e64 v97, v96, v97, s[2:3]
	v_fma_f32 v96, -v98, v96, v95
	v_cmp_lt_f32_e64 s[2:3], 0, v96
	s_nop 1
	v_cndmask_b32_e64 v96, v97, v98, s[2:3]
	v_mul_f32_e32 v97, 0x37800000, v96
	v_cndmask_b32_e32 v96, v96, v97, vcc
	v_cmp_class_f32_e32 vcc, v95, v94
	s_nop 1
	v_cndmask_b32_e32 v95, v96, v95, vcc
	v_div_scale_f32 v96, s[2:3], v95, v95, s23
	v_rcp_f32_e32 v97, v96
	s_nop 0
	v_fma_f32 v98, -v96, v97, 1.0
	v_fmac_f32_e32 v97, v98, v97
	v_div_scale_f32 v98, vcc, s23, v95, s23
	v_mul_f32_e32 v99, v98, v97
	v_fma_f32 v106, -v96, v99, v98
	v_fmac_f32_e32 v99, v106, v97
	v_fma_f32 v96, -v96, v99, v98
	v_div_fmas_f32 v96, v96, v97, v99
	v_div_fixup_f32 v96, v96, v95, s23
	v_pk_mul_f32 v[98:99], v[96:97], v[100:101] op_sel_hi:[0,1]
	v_pk_mul_f32 v[78:79], v[96:97], v[78:79] op_sel_hi:[0,1]
	v_pk_mul_f32 v[98:99], v[0:1], v[98:99]
	v_pk_mul_f32 v[78:79], v[82:83], v[78:79]
	v_lshlrev_b32_e32 v95, 16, v77
	v_lshlrev_b32_e32 v97, 16, v76
	v_pk_mul_f32 v[98:99], v[98:99], v[104:105]
	v_pk_mul_f32 v[74:75], v[78:79], v[74:75]
	v_mul_f32_e32 v78, 0xbfb8aa3b, v97
	v_and_b32_e32 v104, 0xffff0000, v77
	v_mul_f32_e32 v77, 0xbfb8aa3b, v95
	v_exp_f32_e32 v78, v78
	v_exp_f32_e32 v79, v77
	v_pk_mul_f32 v[100:101], v[96:97], v[102:103] op_sel_hi:[0,1]
	v_and_b32_e32 v105, 0xffff0000, v76
	v_mul_f32_e32 v76, 0xbfb8aa3b, v105
	v_pk_add_f32 v[78:79], v[78:79], 1.0 op_sel_hi:[1,0]
	v_exp_f32_e32 v76, v76
	v_div_scale_f32 v77, s[2:3], v79, v79, v95
	v_rcp_f32_e32 v102, v77
	v_pk_mul_f32 v[80:81], v[96:97], v[80:81] op_sel_hi:[0,1]
	v_pk_mul_f32 v[100:101], v[4:5], v[100:101]
	v_pk_mul_f32 v[80:81], v[84:85], v[80:81]
	v_fma_f32 v103, -v77, v102, 1.0
	v_fmac_f32_e32 v102, v103, v102
	v_div_scale_f32 v103, vcc, v95, v79, v95
	v_mul_f32_e32 v106, v103, v102
	v_fma_f32 v107, -v77, v106, v103
	v_fmac_f32_e32 v106, v107, v102
	v_fma_f32 v77, -v77, v106, v103
	v_div_fmas_f32 v77, v77, v102, v106
	v_div_fixup_f32 v79, v77, v79, v95
	v_div_scale_f32 v77, s[2:3], v78, v78, v97
	v_rcp_f32_e32 v95, v77
	s_nop 0
	v_fma_f32 v102, -v77, v95, 1.0
	v_fmac_f32_e32 v95, v102, v95
	v_div_scale_f32 v102, vcc, v97, v78, v97
	v_mul_f32_e32 v103, v102, v95
	v_fma_f32 v106, -v77, v103, v102
	v_fmac_f32_e32 v103, v106, v95
	v_fma_f32 v77, -v77, v103, v102
	v_div_fmas_f32 v77, v77, v95, v103
	v_div_fixup_f32 v78, v77, v78, v97
	v_mul_f32_e32 v77, 0xbfb8aa3b, v104
	v_exp_f32_e32 v77, v77
	v_pk_mul_f32 v[78:79], v[100:101], v[78:79]
	v_pk_add_f32 v[76:77], v[76:77], 1.0 op_sel_hi:[1,0]
	s_nop 0
	v_div_scale_f32 v95, s[2:3], v77, v77, v104
	v_rcp_f32_e32 v96, v95
	s_nop 0
	v_fma_f32 v97, -v95, v96, 1.0
	v_fmac_f32_e32 v96, v97, v96
	v_div_scale_f32 v97, vcc, v104, v77, v104
	v_mul_f32_e32 v100, v97, v96
	v_fma_f32 v101, -v95, v100, v97
	v_fmac_f32_e32 v100, v101, v96
	v_fma_f32 v95, -v95, v100, v97
	v_div_fmas_f32 v95, v95, v96, v100
	v_div_fixup_f32 v77, v95, v77, v104
	v_div_scale_f32 v95, s[2:3], v76, v76, v105
	v_rcp_f32_e32 v96, v95
	s_nop 0
	v_fma_f32 v97, -v95, v96, 1.0
	v_fmac_f32_e32 v96, v97, v96
	v_div_scale_f32 v97, vcc, v105, v76, v105
	v_mul_f32_e32 v100, v97, v96
	v_fma_f32 v101, -v95, v100, v97
	v_fmac_f32_e32 v100, v101, v96
	v_fma_f32 v95, -v95, v100, v97
	v_div_fmas_f32 v95, v95, v96, v100
	v_div_fixup_f32 v76, v95, v76, v105
	v_pk_mul_f32 v[76:77], v[80:81], v[76:77]
	v_bfe_u32 v95, v75, 16, 1
	v_bfe_u32 v80, v77, 16, 1
	v_bfe_u32 v81, v76, 16, 1
	v_add3_u32 v77, v77, v80, s24
	v_bfe_u32 v80, v98, 16, 1
	v_bfe_u32 v96, v74, 16, 1
	v_add3_u32 v76, v76, v81, s24
	v_bfe_u32 v81, v99, 16, 1
	v_add3_u32 v80, v98, v80, s24
	v_add3_u32 v74, v74, v96, s24
	v_add3_u32 v75, v75, v95, s24
	v_bfe_u32 v95, v78, 16, 1
	v_add3_u32 v81, v99, v81, s24
	v_lshrrev_b32_e32 v80, 16, v80
	v_bfe_u32 v96, v79, 16, 1
	v_add3_u32 v78, v78, v95, s24
	v_lshrrev_b32_e32 v81, 16, v81
	v_and_or_b32 v74, v74, s21, v80
	v_add_co_u32_e32 v80, vcc, s25, v86
	v_add3_u32 v79, v79, v96, s24
	v_lshrrev_b32_e32 v78, 16, v78
	v_and_or_b32 v75, v75, s21, v81
	v_addc_co_u32_e32 v81, vcc, 0, v87, vcc
	v_lshrrev_b32_e32 v79, 16, v79
	v_and_or_b32 v76, v76, s21, v78
	v_add_co_u32_e32 v78, vcc, s26, v86
	v_and_or_b32 v77, v77, s21, v79
	s_nop 0
	v_addc_co_u32_e32 v79, vcc, 0, v87, vcc
	s_waitcnt vmcnt(15)
; __device__ __forceinline__ unsigned pk2(float lo, float hi) { return f2bf(lo) | (f2bf(hi) << 16); }
; __device__ __forceinline__ float silu(float x) { return x / (1.f + __expf(-x)); }
; __global__ void __launch_bounds__(NWAVES * 64, 2) hybrid_fwd(Args args) {
;     ...
;                 po[64 * j] = o;
;                 v4u o2;
; #pragma unroll
;                 for (int e = 0; e < 4; ++e) o2[e] = pk2(bflo(ab[j][e]) * silu(bflo(gm[j][e])), bfhi(ab[j][e]) * silu(bfhi(gm[j][e])));
;                 po[256 + 64 * j] = o2; }
	v_lshlrev_b32_e32 v86, 16, v71
	v_lshlrev_b32_e32 v87, 16, v70
	global_store_dwordx4 v[78:79], v[74:77], off offset:-4096
	v_and_b32_e32 v95, 0xffff0000, v71
	v_mul_f32_e32 v71, 0xbfb8aa3b, v86
	v_mul_f32_e32 v74, 0xbfb8aa3b, v87
	v_exp_f32_e32 v74, v74
	v_exp_f32_e32 v75, v71
	v_and_b32_e32 v96, 0xffff0000, v70
	v_mul_f32_e32 v70, 0xbfb8aa3b, v96
	v_exp_f32_e32 v70, v70
	v_pk_add_f32 v[74:75], v[74:75], 1.0 op_sel_hi:[1,0]
	v_lshlrev_b32_e32 v77, 16, v67
	v_div_scale_f32 v71, s[2:3], v75, v75, v86
	v_rcp_f32_e32 v97, v71
	v_lshlrev_b32_e32 v76, 16, v66
	v_and_b32_e32 v67, 0xffff0000, v67
	v_and_b32_e32 v66, 0xffff0000, v66
	v_fma_f32 v98, -v71, v97, 1.0
	v_fmac_f32_e32 v97, v98, v97
	v_div_scale_f32 v98, vcc, v86, v75, v86
	v_mul_f32_e32 v99, v98, v97
	v_fma_f32 v100, -v71, v99, v98
	v_fmac_f32_e32 v99, v100, v97
	v_fma_f32 v71, -v71, v99, v98
	v_div_fmas_f32 v71, v71, v97, v99
	v_div_fixup_f32 v75, v71, v75, v86
	v_div_scale_f32 v71, s[2:3], v74, v74, v87
	v_rcp_f32_e32 v86, v71
	s_nop 0
	v_fma_f32 v97, -v71, v86, 1.0
	v_fmac_f32_e32 v86, v97, v86
	v_div_scale_f32 v97, vcc, v87, v74, v87
	v_mul_f32_e32 v98, v97, v86
	v_fma_f32 v99, -v71, v98, v97
	v_fmac_f32_e32 v98, v99, v86
	v_fma_f32 v71, -v71, v98, v97
	v_div_fmas_f32 v71, v71, v86, v98
	v_div_fixup_f32 v74, v71, v74, v87
	v_mul_f32_e32 v71, 0xbfb8aa3b, v95
	v_exp_f32_e32 v71, v71
	v_pk_mul_f32 v[74:75], v[74:75], v[76:77]
	v_pk_add_f32 v[70:71], v[70:71], 1.0 op_sel_hi:[1,0]
	s_nop 0
	v_div_scale_f32 v76, s[2:3], v71, v71, v95
	v_rcp_f32_e32 v77, v76
	s_nop 0
	v_fma_f32 v86, -v76, v77, 1.0
	v_fmac_f32_e32 v77, v86, v77
	v_div_scale_f32 v86, vcc, v95, v71, v95
	v_mul_f32_e32 v87, v86, v77
	v_fma_f32 v97, -v76, v87, v86
	v_fmac_f32_e32 v87, v97, v77
	v_fma_f32 v76, -v76, v87, v86
	v_div_fmas_f32 v76, v76, v77, v87
	v_div_fixup_f32 v71, v76, v71, v95
	v_div_scale_f32 v76, s[2:3], v70, v70, v96
	v_rcp_f32_e32 v77, v76
	s_nop 0
	v_fma_f32 v86, -v76, v77, 1.0
	v_fmac_f32_e32 v77, v86, v77
	v_div_scale_f32 v86, vcc, v96, v70, v96
	v_mul_f32_e32 v87, v86, v77
	v_fma_f32 v95, -v76, v87, v86
	v_fmac_f32_e32 v87, v95, v77
	v_fma_f32 v76, -v76, v87, v86
	v_div_fmas_f32 v76, v76, v77, v87
	v_div_fixup_f32 v70, v76, v70, v96
	v_and_b32_e32 v96, 0xffff0000, v72
	v_pk_mul_f32 v[66:67], v[70:71], v[66:67]
	v_lshlrev_b32_e32 v86, 16, v73
	v_lshlrev_b32_e32 v87, 16, v72
	v_mul_f32_e32 v71, 0xbfb8aa3b, v96
	v_mul_f32_e32 v70, 0xbfb8aa3b, v87
	v_exp_f32_e32 v72, v71
	v_mul_f32_e32 v71, 0xbfb8aa3b, v86
	v_exp_f32_e32 v70, v70
	v_exp_f32_e32 v71, v71
	v_and_b32_e32 v95, 0xffff0000, v73
	v_lshlrev_b32_e32 v77, 16, v69
	v_lshlrev_b32_e32 v76, 16, v68
	v_pk_add_f32 v[70:71], v[70:71], 1.0 op_sel_hi:[1,0]
	v_and_b32_e32 v69, 0xffff0000, v69
	v_div_scale_f32 v73, s[2:3], v71, v71, v86
	v_rcp_f32_e32 v97, v73
	v_and_b32_e32 v68, 0xffff0000, v68
	v_fma_f32 v98, -v73, v97, 1.0
	v_fmac_f32_e32 v97, v98, v97
	v_div_scale_f32 v98, vcc, v86, v71, v86
	v_mul_f32_e32 v99, v98, v97
	v_fma_f32 v100, -v73, v99, v98
	v_fmac_f32_e32 v99, v100, v97
	v_fma_f32 v73, -v73, v99, v98
	v_div_fmas_f32 v73, v73, v97, v99
	v_div_fixup_f32 v71, v73, v71, v86
	v_div_scale_f32 v73, s[2:3], v70, v70, v87
	v_rcp_f32_e32 v86, v73
	s_nop 0
	v_fma_f32 v97, -v73, v86, 1.0
	v_fmac_f32_e32 v86, v97, v86
	v_div_scale_f32 v97, vcc, v87, v70, v87
	v_mul_f32_e32 v98, v97, v86
	v_fma_f32 v99, -v73, v98, v97
	v_fmac_f32_e32 v98, v99, v86
	v_fma_f32 v73, -v73, v98, v97
	v_div_fmas_f32 v73, v73, v86, v98
	v_div_fixup_f32 v70, v73, v70, v87
	v_mul_f32_e32 v73, 0xbfb8aa3b, v95
	v_exp_f32_e32 v73, v73
	v_pk_mul_f32 v[70:71], v[70:71], v[76:77]
	v_pk_add_f32 v[72:73], v[72:73], 1.0 op_sel_hi:[1,0]
	s_nop 0
	v_div_scale_f32 v76, s[2:3], v73, v73, v95
	v_rcp_f32_e32 v77, v76
	s_nop 0
	v_fma_f32 v86, -v76, v77, 1.0
	v_fmac_f32_e32 v77, v86, v77
	v_div_scale_f32 v86, vcc, v95, v73, v95
	v_mul_f32_e32 v87, v86, v77
	v_fma_f32 v97, -v76, v87, v86
	v_fmac_f32_e32 v87, v97, v77
	v_fma_f32 v76, -v76, v87, v86
	v_div_fmas_f32 v76, v76, v77, v87
	v_div_fixup_f32 v73, v76, v73, v95
	v_div_scale_f32 v76, s[2:3], v72, v72, v96
	v_rcp_f32_e32 v77, v76
	s_nop 0
	v_fma_f32 v86, -v76, v77, 1.0
	v_fmac_f32_e32 v77, v86, v77
	v_div_scale_f32 v86, vcc, v96, v72, v96
	v_mul_f32_e32 v87, v86, v77
	v_fma_f32 v95, -v76, v87, v86
	v_fmac_f32_e32 v87, v95, v77
	v_fma_f32 v76, -v76, v87, v86
	v_div_fmas_f32 v76, v76, v77, v87
	v_div_fixup_f32 v72, v76, v72, v96
	v_pk_mul_f32 v[68:69], v[72:73], v[68:69]
	v_bfe_u32 v76, v67, 16, 1
	v_bfe_u32 v72, v69, 16, 1
	v_bfe_u32 v73, v68, 16, 1
	v_bfe_u32 v77, v66, 16, 1
	v_add3_u32 v66, v66, v77, s24
	v_add3_u32 v67, v67, v76, s24
	v_add3_u32 v68, v68, v73, s24
	v_add3_u32 v69, v69, v72, s24
	v_bfe_u32 v72, v74, 16, 1
	v_bfe_u32 v73, v75, 16, 1
	v_bfe_u32 v76, v70, 16, 1
	v_bfe_u32 v77, v71, 16, 1
	v_add3_u32 v71, v71, v77, s24
	v_add3_u32 v70, v70, v76, s24
	v_add3_u32 v73, v75, v73, s24
	v_add3_u32 v72, v74, v72, s24
	v_lshrrev_b32_e32 v72, 16, v72
	v_lshrrev_b32_e32 v73, 16, v73
	v_lshrrev_b32_e32 v70, 16, v70
	v_lshrrev_b32_e32 v71, 16, v71
	v_and_or_b32 v69, v69, s21, v71
	v_and_or_b32 v68, v68, s21, v70
	v_and_or_b32 v67, v67, s21, v73
	v_and_or_b32 v66, v66, s21, v72
	s_waitcnt vmcnt(13)
; __device__ __forceinline__ unsigned pk2(float lo, float hi) { return f2bf(lo) | (f2bf(hi) << 16); }
; __device__ __forceinline__ float silu(float x) { return x / (1.f + __expf(-x)); }
; __global__ void __launch_bounds__(NWAVES * 64, 2) hybrid_fwd(Args args) {
;     ...
;             for (int j = 0; j < 4; ++j) { float d[8]; float ss = 0.f;
; #pragma unroll
;                 for (int e = 0; e < 4; ++e) { const float d0 = bflo(a[j][e]) - lam * bflo(b[j][e]), d1 = bfhi(a[j][e]) - lam * bfhi(b[j][e]); d[2 * e] = d0; d[2 * e + 1] = d1; ss += d0 * d0 + d1 * d1; }
;                 ss += __shfl_xor(ss, 1); ss += __shfl_xor(ss, 2); ss += __shfl_xor(ss, 4); ss += __shfl_xor(ss, 8); ss += __shfl_xor(ss, 16);
;                 const float rstd = (1.f - LAMBDA_INIT) / sqrtf(ss * (1.f / 256.f) + RMS_EPS); v4u o;
; #pragma unroll
;                 for (int e = 0; e < 4; ++e) { const f32x4 s4 = (e >> 1) ? sl1 : sl0;
;                     o[e] = pk2(d[2 * e] * rstd * s4[(e & 1) * 2] * silu(bflo(gt[j][e])), d[2 * e + 1] * rstd * s4[(e & 1) * 2 + 1] * silu(bfhi(gt[j][e]))); }
;                 po[64 * j] = o;
	v_and_b32_e32 v76, 0xffff0000, v54
	global_store_dwordx4 v[78:79], v[66:69], off
	v_lshlrev_b32_e32 v70, 16, v62
	v_lshlrev_b32_e32 v71, 16, v63
	v_and_b32_e32 v68, 0xffff0000, v62
	v_and_b32_e32 v69, 0xffff0000, v63
	v_lshlrev_b32_e32 v66, 16, v64
	v_and_b32_e32 v62, 0xffff0000, v64
	v_lshlrev_b32_e32 v67, 16, v65
	v_and_b32_e32 v63, 0xffff0000, v65
	v_lshlrev_b32_e32 v65, 16, v59
	v_lshlrev_b32_e32 v64, 16, v58
	v_lshlrev_b32_e32 v73, 16, v55
	v_lshlrev_b32_e32 v74, 16, v54
	v_mul_f32_e32 v54, 0xbfb8aa3b, v76
	v_pk_fma_f32 v[64:65], v[2:3], v[70:71], v[64:65] neg_lo:[1,0,0] neg_hi:[1,0,0]
	v_mul_f32_e32 v70, 0xbfb8aa3b, v74
	v_exp_f32_e32 v72, v54
	v_mul_f32_e32 v54, 0xbfb8aa3b, v73
	v_exp_f32_e32 v70, v70
	v_exp_f32_e32 v71, v54
	v_and_b32_e32 v75, 0xffff0000, v55
	v_and_b32_e32 v59, 0xffff0000, v59
	v_and_b32_e32 v58, 0xffff0000, v58
	v_pk_add_f32 v[54:55], v[70:71], 1.0 op_sel_hi:[1,0]
	v_pk_fma_f32 v[58:59], v[2:3], v[68:69], v[58:59] neg_lo:[1,0,0] neg_hi:[1,0,0]
	v_div_scale_f32 v70, s[2:3], v55, v55, v73
	v_rcp_f32_e32 v71, v70
	v_pk_mul_f32 v[68:69], v[58:59], v[58:59]
	v_fma_f32 v77, -v70, v71, 1.0
	v_fmac_f32_e32 v71, v77, v71
	v_div_scale_f32 v77, vcc, v73, v55, v73
	v_mul_f32_e32 v86, v77, v71
	v_fma_f32 v87, -v70, v86, v77
	v_fmac_f32_e32 v86, v87, v71
	v_fma_f32 v70, -v70, v86, v77
	v_div_fmas_f32 v70, v70, v71, v86
	v_div_fixup_f32 v55, v70, v55, v73
	v_div_scale_f32 v70, s[2:3], v54, v54, v74
	v_rcp_f32_e32 v71, v70
	v_pk_fma_f32 v[68:69], v[64:65], v[64:65], v[68:69]
	v_fma_f32 v73, -v70, v71, 1.0
	v_fmac_f32_e32 v71, v73, v71
	v_div_scale_f32 v73, vcc, v74, v54, v74
	v_mul_f32_e32 v77, v73, v71
	v_fma_f32 v86, -v70, v77, v73
	v_fmac_f32_e32 v77, v86, v71
	v_fma_f32 v70, -v70, v77, v73
	v_div_fmas_f32 v70, v70, v71, v77
	v_div_fixup_f32 v54, v70, v54, v74
	v_mul_f32_e32 v70, 0xbfb8aa3b, v75
	v_exp_f32_e32 v73, v70
	v_add_f32_e32 v68, v68, v69
	v_pk_add_f32 v[70:71], v[72:73], 1.0 op_sel_hi:[1,0]
	s_nop 0
	v_div_scale_f32 v72, s[2:3], v71, v71, v75
	v_rcp_f32_e32 v73, v72
	s_nop 0
	v_fma_f32 v74, -v72, v73, 1.0
	v_fmac_f32_e32 v73, v74, v73
	v_div_scale_f32 v74, vcc, v75, v71, v75
	v_mul_f32_e32 v77, v74, v73
	v_fma_f32 v86, -v72, v77, v74
	v_fmac_f32_e32 v77, v86, v73
	v_fma_f32 v72, -v72, v77, v74
	v_div_fmas_f32 v72, v72, v73, v77
	v_div_fixup_f32 v71, v72, v71, v75
	v_div_scale_f32 v72, s[2:3], v70, v70, v76
	v_rcp_f32_e32 v73, v72
	s_nop 0
	v_fma_f32 v74, -v72, v73, 1.0
	v_fmac_f32_e32 v73, v74, v73
	v_div_scale_f32 v74, vcc, v76, v70, v76
	v_mul_f32_e32 v75, v74, v73
	v_fma_f32 v77, -v72, v75, v74
	v_fmac_f32_e32 v75, v77, v73
	v_fma_f32 v72, -v72, v75, v74
	v_div_fmas_f32 v72, v72, v73, v75
	v_div_fixup_f32 v70, v72, v70, v76
	v_lshlrev_b32_e32 v73, 16, v61
	v_lshlrev_b32_e32 v72, 16, v60
	v_and_b32_e32 v61, 0xffff0000, v61
	v_and_b32_e32 v60, 0xffff0000, v60
	v_pk_fma_f32 v[60:61], v[2:3], v[62:63], v[60:61] neg_lo:[1,0,0] neg_hi:[1,0,0]
	v_pk_fma_f32 v[66:67], v[2:3], v[66:67], v[72:73] neg_lo:[1,0,0] neg_hi:[1,0,0]
	v_pk_mul_f32 v[62:63], v[60:61], v[60:61]
	s_nop 0
	v_pk_fma_f32 v[62:63], v[66:67], v[66:67], v[62:63]
	s_nop 0
	v_add_f32_e32 v62, v68, v62
	v_add_f32_e32 v62, v62, v63
	ds_bpermute_b32 v63, v88, v62
	s_waitcnt lgkmcnt(0)
	v_add_f32_e32 v62, v62, v63
	ds_bpermute_b32 v63, v89, v62
	s_waitcnt lgkmcnt(0)
	v_add_f32_e32 v62, v62, v63
	ds_bpermute_b32 v63, v90, v62
	s_waitcnt lgkmcnt(0)
	v_add_f32_e32 v62, v62, v63
	ds_bpermute_b32 v63, v91, v62
	s_waitcnt lgkmcnt(0)
	v_add_f32_e32 v62, v62, v63
	ds_bpermute_b32 v63, v92, v62
	s_waitcnt lgkmcnt(0)
	v_add_f32_e32 v62, v62, v63
	v_fmamk_f32 v62, v62, 0x3b800000, v93
	v_cmp_gt_f32_e32 vcc, s22, v62
	v_mul_f32_e32 v63, 0x4f800000, v62
	s_nop 0
	v_cndmask_b32_e32 v62, v62, v63, vcc
	v_sqrt_f32_e32 v63, v62
	s_nop 0
	v_add_u32_e32 v68, -1, v63
	v_fma_f32 v69, -v68, v63, v62
	v_cmp_ge_f32_e64 s[2:3], 0, v69
	v_add_u32_e32 v69, 1, v63
	s_nop 0
	v_cndmask_b32_e64 v68, v63, v68, s[2:3]
	v_fma_f32 v63, -v69, v63, v62
	v_cmp_lt_f32_e64 s[2:3], 0, v63
	s_nop 1
	v_cndmask_b32_e64 v63, v68, v69, s[2:3]
	v_mul_f32_e32 v68, 0x37800000, v63
	v_cndmask_b32_e32 v63, v63, v68, vcc
	v_cmp_class_f32_e32 vcc, v62, v94
	s_nop 1
	v_cndmask_b32_e32 v62, v63, v62, vcc
	v_div_scale_f32 v63, s[2:3], v62, v62, s23
	v_rcp_f32_e32 v68, v63
	s_nop 0
	v_fma_f32 v69, -v63, v68, 1.0
	v_fmac_f32_e32 v68, v69, v68
	v_div_scale_f32 v69, vcc, s23, v62, s23
	v_mul_f32_e32 v72, v69, v68
	v_fma_f32 v73, -v63, v72, v69
	v_fmac_f32_e32 v72, v73, v68
	v_fma_f32 v63, -v63, v72, v69
	v_div_fmas_f32 v63, v63, v68, v72
	v_div_fixup_f32 v62, v63, v62, s23
	v_pk_mul_f32 v[64:65], v[62:63], v[64:65] op_sel_hi:[0,1]
	v_pk_mul_f32 v[64:65], v[0:1], v[64:65]
	v_pk_mul_f32 v[58:59], v[62:63], v[58:59] op_sel_hi:[0,1]
	v_lshlrev_b32_e32 v63, 16, v57
	v_lshlrev_b32_e32 v68, 16, v56
	v_pk_mul_f32 v[54:55], v[64:65], v[54:55]
	v_mul_f32_e32 v64, 0xbfb8aa3b, v68
	v_and_b32_e32 v69, 0xffff0000, v57
	v_mul_f32_e32 v57, 0xbfb8aa3b, v63
	v_exp_f32_e32 v64, v64
	v_exp_f32_e32 v65, v57
	v_pk_mul_f32 v[58:59], v[82:83], v[58:59]
	v_pk_mul_f32 v[66:67], v[62:63], v[66:67] op_sel_hi:[0,1]
	v_pk_mul_f32 v[58:59], v[58:59], v[70:71]
	v_pk_add_f32 v[64:65], v[64:65], 1.0 op_sel_hi:[1,0]
	v_and_b32_e32 v70, 0xffff0000, v56
	v_div_scale_f32 v57, s[2:3], v65, v65, v63
	v_rcp_f32_e32 v71, v57
	v_mul_f32_e32 v56, 0xbfb8aa3b, v70
	v_exp_f32_e32 v56, v56
	v_pk_mul_f32 v[66:67], v[4:5], v[66:67]
	v_fma_f32 v72, -v57, v71, 1.0
	v_fmac_f32_e32 v71, v72, v71
	v_div_scale_f32 v72, vcc, v63, v65, v63
	v_mul_f32_e32 v73, v72, v71
	v_fma_f32 v74, -v57, v73, v72
	v_fmac_f32_e32 v73, v74, v71
	v_fma_f32 v57, -v57, v73, v72
; __device__ __forceinline__ unsigned pk2(float lo, float hi) { return f2bf(lo) | (f2bf(hi) << 16); }
; __device__ __forceinline__ float silu(float x) { return x / (1.f + __expf(-x)); }
; __global__ void __launch_bounds__(NWAVES * 64, 2) hybrid_fwd(Args args) {
;     ...
;                 const float rstd = (1.f - LAMBDA_INIT) / sqrtf(ss * (1.f / 256.f) + RMS_EPS); v4u o;
; #pragma unroll
;                 for (int e = 0; e < 4; ++e) { const f32x4 s4 = (e >> 1) ? sl1 : sl0;
;                     o[e] = pk2(d[2 * e] * rstd * s4[(e & 1) * 2] * silu(bflo(gt[j][e])), d[2 * e + 1] * rstd * s4[(e & 1) * 2 + 1] * silu(bfhi(gt[j][e]))); }
;                 po[64 * j] = o;
;                 v4u o2;
; #pragma unroll
;                 for (int e = 0; e < 4; ++e) o2[e] = pk2(bflo(ab[j][e]) * silu(bflo(gm[j][e])), bfhi(ab[j][e]) * silu(bfhi(gm[j][e])));
;                 po[256 + 64 * j] = o2; }
	v_div_fmas_f32 v57, v57, v71, v73
	v_div_fixup_f32 v65, v57, v65, v63
	v_div_scale_f32 v57, s[2:3], v64, v64, v68
	v_rcp_f32_e32 v63, v57
	s_nop 0
	v_fma_f32 v71, -v57, v63, 1.0
	v_fmac_f32_e32 v63, v71, v63
	v_div_scale_f32 v71, vcc, v68, v64, v68
	v_mul_f32_e32 v72, v71, v63
	v_fma_f32 v73, -v57, v72, v71
	v_fmac_f32_e32 v72, v73, v63
	v_fma_f32 v57, -v57, v72, v71
	v_div_fmas_f32 v57, v57, v63, v72
	v_div_fixup_f32 v64, v57, v64, v68
	v_mul_f32_e32 v57, 0xbfb8aa3b, v69
	v_exp_f32_e32 v57, v57
	v_pk_mul_f32 v[60:61], v[62:63], v[60:61] op_sel_hi:[0,1]
	v_pk_mul_f32 v[64:65], v[66:67], v[64:65]
	v_pk_mul_f32 v[60:61], v[84:85], v[60:61]
	v_pk_add_f32 v[56:57], v[56:57], 1.0 op_sel_hi:[1,0]
	s_nop 0
	v_div_scale_f32 v62, s[2:3], v57, v57, v69
	v_rcp_f32_e32 v63, v62
	s_nop 0
	v_fma_f32 v66, -v62, v63, 1.0
	v_fmac_f32_e32 v63, v66, v63
	v_div_scale_f32 v66, vcc, v69, v57, v69
	v_mul_f32_e32 v67, v66, v63
	v_fma_f32 v68, -v62, v67, v66
	v_fmac_f32_e32 v67, v68, v63
	v_fma_f32 v62, -v62, v67, v66
	v_div_fmas_f32 v62, v62, v63, v67
	v_div_fixup_f32 v57, v62, v57, v69
	v_div_scale_f32 v62, s[2:3], v56, v56, v70
	v_rcp_f32_e32 v63, v62
	s_nop 0
	v_fma_f32 v66, -v62, v63, 1.0
	v_fmac_f32_e32 v63, v66, v63
	v_div_scale_f32 v66, vcc, v70, v56, v70
	v_mul_f32_e32 v67, v66, v63
	v_fma_f32 v68, -v62, v67, v66
	v_fmac_f32_e32 v67, v68, v63
	v_fma_f32 v62, -v62, v67, v66
	v_div_fmas_f32 v62, v62, v63, v67
	v_div_fixup_f32 v56, v62, v56, v70
	v_pk_mul_f32 v[56:57], v[60:61], v[56:57]
	v_bfe_u32 v62, v59, 16, 1
	v_bfe_u32 v60, v57, 16, 1
	v_bfe_u32 v61, v56, 16, 1
	v_bfe_u32 v63, v58, 16, 1
	v_add3_u32 v58, v58, v63, s24
	v_add3_u32 v59, v59, v62, s24
	v_add3_u32 v56, v56, v61, s24
	v_add3_u32 v57, v57, v60, s24
	v_bfe_u32 v60, v54, 16, 1
	v_bfe_u32 v61, v55, 16, 1
	v_bfe_u32 v62, v64, 16, 1
	v_bfe_u32 v63, v65, 16, 1
	v_add3_u32 v63, v65, v63, s24
	v_add3_u32 v62, v64, v62, s24
	v_add3_u32 v55, v55, v61, s24
	v_add3_u32 v54, v54, v60, s24
	v_lshrrev_b32_e32 v54, 16, v54
	v_lshrrev_b32_e32 v55, 16, v55
	v_lshrrev_b32_e32 v60, 16, v62
	v_lshrrev_b32_e32 v61, 16, v63
	v_and_or_b32 v57, v57, s21, v61
	v_and_or_b32 v56, v56, s21, v60
	v_and_or_b32 v55, v59, s21, v55
	v_and_or_b32 v54, v58, s21, v54
	s_waitcnt vmcnt(12)
	v_lshlrev_b32_e32 v58, 16, v51
	v_lshlrev_b32_e32 v59, 16, v50
	global_store_dwordx4 v[80:81], v[54:57], off offset:1024
	v_and_b32_e32 v60, 0xffff0000, v51
	v_mul_f32_e32 v51, 0xbfb8aa3b, v58
	v_mul_f32_e32 v54, 0xbfb8aa3b, v59
	v_exp_f32_e32 v54, v54
	v_exp_f32_e32 v55, v51
	v_and_b32_e32 v61, 0xffff0000, v50
	v_mul_f32_e32 v50, 0xbfb8aa3b, v61
	v_exp_f32_e32 v50, v50
	v_pk_add_f32 v[54:55], v[54:55], 1.0 op_sel_hi:[1,0]
	v_lshlrev_b32_e32 v57, 16, v47
	v_div_scale_f32 v51, s[2:3], v55, v55, v58
	v_rcp_f32_e32 v62, v51
	v_lshlrev_b32_e32 v56, 16, v46
	v_and_b32_e32 v47, 0xffff0000, v47
	v_and_b32_e32 v46, 0xffff0000, v46
	v_fma_f32 v63, -v51, v62, 1.0
	v_fmac_f32_e32 v62, v63, v62
	v_div_scale_f32 v63, vcc, v58, v55, v58
	v_mul_f32_e32 v64, v63, v62
	v_fma_f32 v65, -v51, v64, v63
	v_fmac_f32_e32 v64, v65, v62
	v_fma_f32 v51, -v51, v64, v63
	v_div_fmas_f32 v51, v51, v62, v64
	v_div_fixup_f32 v55, v51, v55, v58
	v_div_scale_f32 v51, s[2:3], v54, v54, v59
	v_rcp_f32_e32 v58, v51
	s_nop 0
	v_fma_f32 v62, -v51, v58, 1.0
	v_fmac_f32_e32 v58, v62, v58
	v_div_scale_f32 v62, vcc, v59, v54, v59
	v_mul_f32_e32 v63, v62, v58
	v_fma_f32 v64, -v51, v63, v62
	v_fmac_f32_e32 v63, v64, v58
	v_fma_f32 v51, -v51, v63, v62
	v_div_fmas_f32 v51, v51, v58, v63
	v_div_fixup_f32 v54, v51, v54, v59
	v_mul_f32_e32 v51, 0xbfb8aa3b, v60
	v_exp_f32_e32 v51, v51
	v_pk_mul_f32 v[54:55], v[54:55], v[56:57]
	v_pk_add_f32 v[50:51], v[50:51], 1.0 op_sel_hi:[1,0]
	s_nop 0
	v_div_scale_f32 v56, s[2:3], v51, v51, v60
	v_rcp_f32_e32 v57, v56
	s_nop 0
	v_fma_f32 v58, -v56, v57, 1.0
	v_fmac_f32_e32 v57, v58, v57
	v_div_scale_f32 v58, vcc, v60, v51, v60
	v_mul_f32_e32 v59, v58, v57
	v_fma_f32 v62, -v56, v59, v58
	v_fmac_f32_e32 v59, v62, v57
	v_fma_f32 v56, -v56, v59, v58
	v_div_fmas_f32 v56, v56, v57, v59
	v_div_fixup_f32 v51, v56, v51, v60
	v_div_scale_f32 v56, s[2:3], v50, v50, v61
	v_rcp_f32_e32 v57, v56
	s_nop 0
	v_fma_f32 v58, -v56, v57, 1.0
	v_fmac_f32_e32 v57, v58, v57
	v_div_scale_f32 v58, vcc, v61, v50, v61
	v_mul_f32_e32 v59, v58, v57
	v_fma_f32 v60, -v56, v59, v58
	v_fmac_f32_e32 v59, v60, v57
	v_fma_f32 v56, -v56, v59, v58
	v_div_fmas_f32 v56, v56, v57, v59
	v_div_fixup_f32 v50, v56, v50, v61
	v_and_b32_e32 v61, 0xffff0000, v52
	v_pk_mul_f32 v[46:47], v[50:51], v[46:47]
	v_lshlrev_b32_e32 v58, 16, v53
	v_lshlrev_b32_e32 v59, 16, v52
	v_mul_f32_e32 v51, 0xbfb8aa3b, v61
	v_mul_f32_e32 v50, 0xbfb8aa3b, v59
	v_exp_f32_e32 v52, v51
	v_mul_f32_e32 v51, 0xbfb8aa3b, v58
	v_exp_f32_e32 v50, v50
	v_exp_f32_e32 v51, v51
	v_and_b32_e32 v60, 0xffff0000, v53
	v_lshlrev_b32_e32 v57, 16, v49
	v_lshlrev_b32_e32 v56, 16, v48
	v_pk_add_f32 v[50:51], v[50:51], 1.0 op_sel_hi:[1,0]
	v_and_b32_e32 v49, 0xffff0000, v49
	v_div_scale_f32 v53, s[2:3], v51, v51, v58
	v_rcp_f32_e32 v62, v53
	v_and_b32_e32 v48, 0xffff0000, v48
	v_fma_f32 v63, -v53, v62, 1.0
	v_fmac_f32_e32 v62, v63, v62
	v_div_scale_f32 v63, vcc, v58, v51, v58
	v_mul_f32_e32 v64, v63, v62
	v_fma_f32 v65, -v53, v64, v63
	v_fmac_f32_e32 v64, v65, v62
	v_fma_f32 v53, -v53, v64, v63
	v_div_fmas_f32 v53, v53, v62, v64
	v_div_fixup_f32 v51, v53, v51, v58
	v_div_scale_f32 v53, s[2:3], v50, v50, v59
	v_rcp_f32_e32 v58, v53
	s_nop 0
	v_fma_f32 v62, -v53, v58, 1.0
	v_fmac_f32_e32 v58, v62, v58
	v_div_scale_f32 v62, vcc, v59, v50, v59
	v_mul_f32_e32 v63, v62, v58
	v_fma_f32 v64, -v53, v63, v62
	v_fmac_f32_e32 v63, v64, v58
; __device__ __forceinline__ unsigned pk2(float lo, float hi) { return f2bf(lo) | (f2bf(hi) << 16); }
; __device__ __forceinline__ float silu(float x) { return x / (1.f + __expf(-x)); }
; __global__ void __launch_bounds__(NWAVES * 64, 2) hybrid_fwd(Args args) {
;     ...
;             for (int j = 0; j < 4; ++j) { float d[8]; float ss = 0.f;
; #pragma unroll
;                 for (int e = 0; e < 4; ++e) { const float d0 = bflo(a[j][e]) - lam * bflo(b[j][e]), d1 = bfhi(a[j][e]) - lam * bfhi(b[j][e]); d[2 * e] = d0; d[2 * e + 1] = d1; ss += d0 * d0 + d1 * d1; }
;                 ss += __shfl_xor(ss, 1); ss += __shfl_xor(ss, 2); ss += __shfl_xor(ss, 4); ss += __shfl_xor(ss, 8); ss += __shfl_xor(ss, 16);
;                 const float rstd = (1.f - LAMBDA_INIT) / sqrtf(ss * (1.f / 256.f) + RMS_EPS); v4u o;
; #pragma unroll
;                 for (int e = 0; e < 4; ++e) { const f32x4 s4 = (e >> 1) ? sl1 : sl0;
;                     o[e] = pk2(d[2 * e] * rstd * s4[(e & 1) * 2] * silu(bflo(gt[j][e])), d[2 * e + 1] * rstd * s4[(e & 1) * 2 + 1] * silu(bfhi(gt[j][e]))); }
;                 po[64 * j] = o;
;                 v4u o2;
; #pragma unroll
;                 for (int e = 0; e < 4; ++e) o2[e] = pk2(bflo(ab[j][e]) * silu(bflo(gm[j][e])), bfhi(ab[j][e]) * silu(bfhi(gm[j][e])));
;                 po[256 + 64 * j] = o2; }
	v_fma_f32 v53, -v53, v63, v62
	v_div_fmas_f32 v53, v53, v58, v63
	v_div_fixup_f32 v50, v53, v50, v59
	v_mul_f32_e32 v53, 0xbfb8aa3b, v60
	v_exp_f32_e32 v53, v53
	v_pk_mul_f32 v[50:51], v[50:51], v[56:57]
	v_pk_add_f32 v[52:53], v[52:53], 1.0 op_sel_hi:[1,0]
	s_nop 0
	v_div_scale_f32 v56, s[2:3], v53, v53, v60
	v_rcp_f32_e32 v57, v56
	s_nop 0
	v_fma_f32 v58, -v56, v57, 1.0
	v_fmac_f32_e32 v57, v58, v57
	v_div_scale_f32 v58, vcc, v60, v53, v60
	v_mul_f32_e32 v59, v58, v57
	v_fma_f32 v62, -v56, v59, v58
	v_fmac_f32_e32 v59, v62, v57
	v_fma_f32 v56, -v56, v59, v58
	v_div_fmas_f32 v56, v56, v57, v59
	v_div_fixup_f32 v53, v56, v53, v60
	v_div_scale_f32 v56, s[2:3], v52, v52, v61
	v_rcp_f32_e32 v57, v56
	s_nop 0
	v_fma_f32 v58, -v56, v57, 1.0
	v_fmac_f32_e32 v57, v58, v57
	v_div_scale_f32 v58, vcc, v61, v52, v61
	v_mul_f32_e32 v59, v58, v57
	v_fma_f32 v60, -v56, v59, v58
	v_fmac_f32_e32 v59, v60, v57
	v_fma_f32 v56, -v56, v59, v58
	v_div_fmas_f32 v56, v56, v57, v59
	v_div_fixup_f32 v52, v56, v52, v61
	v_pk_mul_f32 v[48:49], v[52:53], v[48:49]
	v_bfe_u32 v56, v47, 16, 1
	v_bfe_u32 v52, v49, 16, 1
	v_bfe_u32 v53, v48, 16, 1
	v_bfe_u32 v57, v46, 16, 1
	v_add3_u32 v46, v46, v57, s24
	v_add3_u32 v47, v47, v56, s24
	v_add3_u32 v48, v48, v53, s24
	v_add3_u32 v49, v49, v52, s24
	v_bfe_u32 v52, v54, 16, 1
	v_bfe_u32 v53, v55, 16, 1
	v_bfe_u32 v56, v50, 16, 1
	v_bfe_u32 v57, v51, 16, 1
	v_add3_u32 v51, v51, v57, s24
	v_add3_u32 v50, v50, v56, s24
	v_add3_u32 v53, v55, v53, s24
	v_add3_u32 v52, v54, v52, s24
	v_lshrrev_b32_e32 v52, 16, v52
	v_lshrrev_b32_e32 v53, 16, v53
	v_lshrrev_b32_e32 v50, 16, v50
	v_lshrrev_b32_e32 v51, 16, v51
	v_and_or_b32 v49, v49, s21, v51
	v_and_or_b32 v48, v48, s21, v50
	v_and_or_b32 v47, v47, s21, v53
	v_and_or_b32 v46, v46, s21, v52
	s_waitcnt vmcnt(10)
	v_and_b32_e32 v56, 0xffff0000, v34
	global_store_dwordx4 v[78:79], v[46:49], off offset:1024
	v_lshlrev_b32_e32 v50, 16, v42
	v_lshlrev_b32_e32 v51, 16, v43
	v_and_b32_e32 v48, 0xffff0000, v42
	v_and_b32_e32 v49, 0xffff0000, v43
	v_lshlrev_b32_e32 v46, 16, v44
	v_and_b32_e32 v42, 0xffff0000, v44
	v_lshlrev_b32_e32 v47, 16, v45
	v_and_b32_e32 v43, 0xffff0000, v45
	v_lshlrev_b32_e32 v45, 16, v39
	v_lshlrev_b32_e32 v44, 16, v38
	v_lshlrev_b32_e32 v53, 16, v35
	v_lshlrev_b32_e32 v54, 16, v34
	v_mul_f32_e32 v34, 0xbfb8aa3b, v56
	v_pk_fma_f32 v[44:45], v[2:3], v[50:51], v[44:45] neg_lo:[1,0,0] neg_hi:[1,0,0]
	v_mul_f32_e32 v50, 0xbfb8aa3b, v54
	v_exp_f32_e32 v52, v34
	v_mul_f32_e32 v34, 0xbfb8aa3b, v53
	v_exp_f32_e32 v50, v50
	v_exp_f32_e32 v51, v34
	v_and_b32_e32 v55, 0xffff0000, v35
	v_and_b32_e32 v39, 0xffff0000, v39
	v_and_b32_e32 v38, 0xffff0000, v38
	v_pk_add_f32 v[34:35], v[50:51], 1.0 op_sel_hi:[1,0]
	v_pk_fma_f32 v[38:39], v[2:3], v[48:49], v[38:39] neg_lo:[1,0,0] neg_hi:[1,0,0]
	v_div_scale_f32 v50, s[2:3], v35, v35, v53
	v_rcp_f32_e32 v51, v50
	v_pk_mul_f32 v[48:49], v[38:39], v[38:39]
	v_fma_f32 v57, -v50, v51, 1.0
	v_fmac_f32_e32 v51, v57, v51
	v_div_scale_f32 v57, vcc, v53, v35, v53
	v_mul_f32_e32 v58, v57, v51
	v_fma_f32 v59, -v50, v58, v57
	v_fmac_f32_e32 v58, v59, v51
	v_fma_f32 v50, -v50, v58, v57
	v_div_fmas_f32 v50, v50, v51, v58
	v_div_fixup_f32 v35, v50, v35, v53
	v_div_scale_f32 v50, s[2:3], v34, v34, v54
	v_rcp_f32_e32 v51, v50
	v_pk_fma_f32 v[48:49], v[44:45], v[44:45], v[48:49]
	v_fma_f32 v53, -v50, v51, 1.0
	v_fmac_f32_e32 v51, v53, v51
	v_div_scale_f32 v53, vcc, v54, v34, v54
	v_mul_f32_e32 v57, v53, v51
	v_fma_f32 v58, -v50, v57, v53
	v_fmac_f32_e32 v57, v58, v51
	v_fma_f32 v50, -v50, v57, v53
	v_div_fmas_f32 v50, v50, v51, v57
	v_div_fixup_f32 v34, v50, v34, v54
	v_mul_f32_e32 v50, 0xbfb8aa3b, v55
	v_exp_f32_e32 v53, v50
	v_add_f32_e32 v48, v48, v49
	v_pk_add_f32 v[50:51], v[52:53], 1.0 op_sel_hi:[1,0]
	s_nop 0
	v_div_scale_f32 v52, s[2:3], v51, v51, v55
	v_rcp_f32_e32 v53, v52
	s_nop 0
	v_fma_f32 v54, -v52, v53, 1.0
	v_fmac_f32_e32 v53, v54, v53
	v_div_scale_f32 v54, vcc, v55, v51, v55
	v_mul_f32_e32 v57, v54, v53
	v_fma_f32 v58, -v52, v57, v54
	v_fmac_f32_e32 v57, v58, v53
	v_fma_f32 v52, -v52, v57, v54
	v_div_fmas_f32 v52, v52, v53, v57
	v_div_fixup_f32 v51, v52, v51, v55
	v_div_scale_f32 v52, s[2:3], v50, v50, v56
	v_rcp_f32_e32 v53, v52
	s_nop 0
	v_fma_f32 v54, -v52, v53, 1.0
	v_fmac_f32_e32 v53, v54, v53
	v_div_scale_f32 v54, vcc, v56, v50, v56
	v_mul_f32_e32 v55, v54, v53
	v_fma_f32 v57, -v52, v55, v54
	v_fmac_f32_e32 v55, v57, v53
	v_fma_f32 v52, -v52, v55, v54
	v_div_fmas_f32 v52, v52, v53, v55
	v_div_fixup_f32 v50, v52, v50, v56
	v_lshlrev_b32_e32 v53, 16, v41
	v_lshlrev_b32_e32 v52, 16, v40
	v_and_b32_e32 v41, 0xffff0000, v41
	v_and_b32_e32 v40, 0xffff0000, v40
	v_pk_fma_f32 v[40:41], v[2:3], v[42:43], v[40:41] neg_lo:[1,0,0] neg_hi:[1,0,0]
	v_pk_fma_f32 v[46:47], v[2:3], v[46:47], v[52:53] neg_lo:[1,0,0] neg_hi:[1,0,0]
	v_pk_mul_f32 v[42:43], v[40:41], v[40:41]
	s_nop 0
	v_pk_fma_f32 v[42:43], v[46:47], v[46:47], v[42:43]
	s_nop 0
	v_add_f32_e32 v42, v48, v42
	v_add_f32_e32 v42, v42, v43
	ds_bpermute_b32 v43, v88, v42
	s_waitcnt lgkmcnt(0)
	v_add_f32_e32 v42, v42, v43
	ds_bpermute_b32 v43, v89, v42
	s_waitcnt lgkmcnt(0)
	v_add_f32_e32 v42, v42, v43
	ds_bpermute_b32 v43, v90, v42
	s_waitcnt lgkmcnt(0)
	v_add_f32_e32 v42, v42, v43
	ds_bpermute_b32 v43, v91, v42
	s_waitcnt lgkmcnt(0)
	v_add_f32_e32 v42, v42, v43
	ds_bpermute_b32 v43, v92, v42
	s_waitcnt lgkmcnt(0)
; __device__ __forceinline__ unsigned pk2(float lo, float hi) { return f2bf(lo) | (f2bf(hi) << 16); }
; __device__ __forceinline__ float silu(float x) { return x / (1.f + __expf(-x)); }
; __global__ void __launch_bounds__(NWAVES * 64, 2) hybrid_fwd(Args args) {
;     ...
;                 const float rstd = (1.f - LAMBDA_INIT) / sqrtf(ss * (1.f / 256.f) + RMS_EPS); v4u o;
; #pragma unroll
;                 for (int e = 0; e < 4; ++e) { const f32x4 s4 = (e >> 1) ? sl1 : sl0;
;                     o[e] = pk2(d[2 * e] * rstd * s4[(e & 1) * 2] * silu(bflo(gt[j][e])), d[2 * e + 1] * rstd * s4[(e & 1) * 2 + 1] * silu(bfhi(gt[j][e]))); }
;                 po[64 * j] = o;
	v_add_f32_e32 v42, v42, v43
	v_fmamk_f32 v42, v42, 0x3b800000, v93
	v_cmp_gt_f32_e32 vcc, s22, v42
	v_mul_f32_e32 v43, 0x4f800000, v42
	s_nop 0
	v_cndmask_b32_e32 v42, v42, v43, vcc
	v_sqrt_f32_e32 v43, v42
	s_nop 0
	v_add_u32_e32 v48, -1, v43
	v_fma_f32 v49, -v48, v43, v42
	v_cmp_ge_f32_e64 s[2:3], 0, v49
	v_add_u32_e32 v49, 1, v43
	s_nop 0
	v_cndmask_b32_e64 v48, v43, v48, s[2:3]
	v_fma_f32 v43, -v49, v43, v42
	v_cmp_lt_f32_e64 s[2:3], 0, v43
	s_nop 1
	v_cndmask_b32_e64 v43, v48, v49, s[2:3]
	v_mul_f32_e32 v48, 0x37800000, v43
	v_cndmask_b32_e32 v43, v43, v48, vcc
	v_cmp_class_f32_e32 vcc, v42, v94
	s_nop 1
	v_cndmask_b32_e32 v42, v43, v42, vcc
	v_div_scale_f32 v43, s[2:3], v42, v42, s23
	v_rcp_f32_e32 v48, v43
	s_nop 0
	v_fma_f32 v49, -v43, v48, 1.0
	v_fmac_f32_e32 v48, v49, v48
	v_div_scale_f32 v49, vcc, s23, v42, s23
	v_mul_f32_e32 v52, v49, v48
	v_fma_f32 v53, -v43, v52, v49
	v_fmac_f32_e32 v52, v53, v48
	v_fma_f32 v43, -v43, v52, v49
	v_div_fmas_f32 v43, v43, v48, v52
	v_div_fixup_f32 v42, v43, v42, s23
	v_pk_mul_f32 v[44:45], v[42:43], v[44:45] op_sel_hi:[0,1]
	v_pk_mul_f32 v[44:45], v[0:1], v[44:45]
	v_pk_mul_f32 v[38:39], v[42:43], v[38:39] op_sel_hi:[0,1]
	v_lshlrev_b32_e32 v43, 16, v37
	v_lshlrev_b32_e32 v48, 16, v36
	v_pk_mul_f32 v[34:35], v[44:45], v[34:35]
	v_mul_f32_e32 v44, 0xbfb8aa3b, v48
	v_and_b32_e32 v49, 0xffff0000, v37
	v_mul_f32_e32 v37, 0xbfb8aa3b, v43
	v_exp_f32_e32 v44, v44
	v_exp_f32_e32 v45, v37
	v_pk_mul_f32 v[38:39], v[82:83], v[38:39]
	v_pk_mul_f32 v[46:47], v[42:43], v[46:47] op_sel_hi:[0,1]
	v_pk_mul_f32 v[38:39], v[38:39], v[50:51]
	v_pk_add_f32 v[44:45], v[44:45], 1.0 op_sel_hi:[1,0]
	v_and_b32_e32 v50, 0xffff0000, v36
	v_div_scale_f32 v37, s[2:3], v45, v45, v43
	v_rcp_f32_e32 v51, v37
	v_mul_f32_e32 v36, 0xbfb8aa3b, v50
	v_exp_f32_e32 v36, v36
	v_pk_mul_f32 v[46:47], v[4:5], v[46:47]
	v_fma_f32 v52, -v37, v51, 1.0
	v_fmac_f32_e32 v51, v52, v51
	v_div_scale_f32 v52, vcc, v43, v45, v43
	v_mul_f32_e32 v53, v52, v51
	v_fma_f32 v54, -v37, v53, v52
	v_fmac_f32_e32 v53, v54, v51
	v_fma_f32 v37, -v37, v53, v52
	v_div_fmas_f32 v37, v37, v51, v53
	v_div_fixup_f32 v45, v37, v45, v43
	v_div_scale_f32 v37, s[2:3], v44, v44, v48
	v_rcp_f32_e32 v43, v37
	s_nop 0
	v_fma_f32 v51, -v37, v43, 1.0
	v_fmac_f32_e32 v43, v51, v43
	v_div_scale_f32 v51, vcc, v48, v44, v48
	v_mul_f32_e32 v52, v51, v43
	v_fma_f32 v53, -v37, v52, v51
	v_fmac_f32_e32 v52, v53, v43
	v_fma_f32 v37, -v37, v52, v51
	v_div_fmas_f32 v37, v37, v43, v52
	v_div_fixup_f32 v44, v37, v44, v48
	v_mul_f32_e32 v37, 0xbfb8aa3b, v49
	v_exp_f32_e32 v37, v37
	v_pk_mul_f32 v[40:41], v[42:43], v[40:41] op_sel_hi:[0,1]
	v_pk_mul_f32 v[44:45], v[46:47], v[44:45]
	v_pk_mul_f32 v[40:41], v[84:85], v[40:41]
	v_pk_add_f32 v[36:37], v[36:37], 1.0 op_sel_hi:[1,0]
	s_nop 0
	v_div_scale_f32 v42, s[2:3], v37, v37, v49
	v_rcp_f32_e32 v43, v42
	s_nop 0
	v_fma_f32 v46, -v42, v43, 1.0
	v_fmac_f32_e32 v43, v46, v43
	v_div_scale_f32 v46, vcc, v49, v37, v49
	v_mul_f32_e32 v47, v46, v43
	v_fma_f32 v48, -v42, v47, v46
	v_fmac_f32_e32 v47, v48, v43
	v_fma_f32 v42, -v42, v47, v46
	v_div_fmas_f32 v42, v42, v43, v47
	v_div_fixup_f32 v37, v42, v37, v49
	v_div_scale_f32 v42, s[2:3], v36, v36, v50
	v_rcp_f32_e32 v43, v42
	s_nop 0
	v_fma_f32 v46, -v42, v43, 1.0
	v_fmac_f32_e32 v43, v46, v43
	v_div_scale_f32 v46, vcc, v50, v36, v50
	v_mul_f32_e32 v47, v46, v43
	v_fma_f32 v48, -v42, v47, v46
	v_fmac_f32_e32 v47, v48, v43
	v_fma_f32 v42, -v42, v47, v46
	v_div_fmas_f32 v42, v42, v43, v47
	v_div_fixup_f32 v36, v42, v36, v50
	v_pk_mul_f32 v[36:37], v[40:41], v[36:37]
	v_bfe_u32 v42, v39, 16, 1
	v_bfe_u32 v40, v37, 16, 1
	v_bfe_u32 v41, v36, 16, 1
	v_bfe_u32 v43, v38, 16, 1
	v_add3_u32 v38, v38, v43, s24
	v_add3_u32 v39, v39, v42, s24
	v_add3_u32 v36, v36, v41, s24
	v_add3_u32 v37, v37, v40, s24
	v_bfe_u32 v40, v34, 16, 1
	v_bfe_u32 v41, v35, 16, 1
	v_bfe_u32 v42, v44, 16, 1
	v_bfe_u32 v43, v45, 16, 1
	v_add3_u32 v43, v45, v43, s24
	v_add3_u32 v42, v44, v42, s24
	v_add3_u32 v35, v35, v41, s24
	v_add3_u32 v34, v34, v40, s24
	v_lshrrev_b32_e32 v34, 16, v34
	v_lshrrev_b32_e32 v35, 16, v35
	v_lshrrev_b32_e32 v40, 16, v42
	v_lshrrev_b32_e32 v41, 16, v43
	v_and_or_b32 v37, v37, s21, v41
	v_and_or_b32 v36, v36, s21, v40
	v_and_or_b32 v35, v39, s21, v35
	v_and_or_b32 v34, v38, s21, v34
	s_waitcnt vmcnt(9)
; __device__ __forceinline__ unsigned pk2(float lo, float hi) { return f2bf(lo) | (f2bf(hi) << 16); }
; __device__ __forceinline__ float silu(float x) { return x / (1.f + __expf(-x)); }
; __global__ void __launch_bounds__(NWAVES * 64, 2) hybrid_fwd(Args args) {
;     ...
;                     o[e] = pk2(d[2 * e] * rstd * s4[(e & 1) * 2] * silu(bflo(gt[j][e])), d[2 * e + 1] * rstd * s4[(e & 1) * 2 + 1] * silu(bfhi(gt[j][e]))); }
;                 po[64 * j] = o;
;                 v4u o2;
; #pragma unroll
;                 for (int e = 0; e < 4; ++e) o2[e] = pk2(bflo(ab[j][e]) * silu(bflo(gm[j][e])), bfhi(ab[j][e]) * silu(bfhi(gm[j][e])));
;                 po[256 + 64 * j] = o2; }
	v_lshlrev_b32_e32 v38, 16, v31
	v_lshlrev_b32_e32 v39, 16, v30
	global_store_dwordx4 v[80:81], v[34:37], off offset:2048
	v_and_b32_e32 v40, 0xffff0000, v31
	v_mul_f32_e32 v31, 0xbfb8aa3b, v38
	v_mul_f32_e32 v34, 0xbfb8aa3b, v39
	v_exp_f32_e32 v34, v34
	v_exp_f32_e32 v35, v31
	v_and_b32_e32 v41, 0xffff0000, v30
	v_mul_f32_e32 v30, 0xbfb8aa3b, v41
	v_exp_f32_e32 v30, v30
	v_pk_add_f32 v[34:35], v[34:35], 1.0 op_sel_hi:[1,0]
	v_lshlrev_b32_e32 v37, 16, v27
	v_div_scale_f32 v31, s[2:3], v35, v35, v38
	v_rcp_f32_e32 v42, v31
	v_lshlrev_b32_e32 v36, 16, v26
	v_and_b32_e32 v27, 0xffff0000, v27
	v_and_b32_e32 v26, 0xffff0000, v26
	v_fma_f32 v43, -v31, v42, 1.0
	v_fmac_f32_e32 v42, v43, v42
	v_div_scale_f32 v43, vcc, v38, v35, v38
	v_mul_f32_e32 v44, v43, v42
	v_fma_f32 v45, -v31, v44, v43
	v_fmac_f32_e32 v44, v45, v42
	v_fma_f32 v31, -v31, v44, v43
	v_div_fmas_f32 v31, v31, v42, v44
	v_div_fixup_f32 v35, v31, v35, v38
	v_div_scale_f32 v31, s[2:3], v34, v34, v39
	v_rcp_f32_e32 v38, v31
	s_nop 0
	v_fma_f32 v42, -v31, v38, 1.0
	v_fmac_f32_e32 v38, v42, v38
	v_div_scale_f32 v42, vcc, v39, v34, v39
	v_mul_f32_e32 v43, v42, v38
	v_fma_f32 v44, -v31, v43, v42
	v_fmac_f32_e32 v43, v44, v38
	v_fma_f32 v31, -v31, v43, v42
	v_div_fmas_f32 v31, v31, v38, v43
	v_div_fixup_f32 v34, v31, v34, v39
	v_mul_f32_e32 v31, 0xbfb8aa3b, v40
	v_exp_f32_e32 v31, v31
	v_pk_mul_f32 v[34:35], v[34:35], v[36:37]
	v_pk_add_f32 v[30:31], v[30:31], 1.0 op_sel_hi:[1,0]
	s_nop 0
	v_div_scale_f32 v36, s[2:3], v31, v31, v40
	v_rcp_f32_e32 v37, v36
	s_nop 0
	v_fma_f32 v38, -v36, v37, 1.0
	v_fmac_f32_e32 v37, v38, v37
	v_div_scale_f32 v38, vcc, v40, v31, v40
	v_mul_f32_e32 v39, v38, v37
	v_fma_f32 v42, -v36, v39, v38
	v_fmac_f32_e32 v39, v42, v37
	v_fma_f32 v36, -v36, v39, v38
	v_div_fmas_f32 v36, v36, v37, v39
	v_div_fixup_f32 v31, v36, v31, v40
	v_div_scale_f32 v36, s[2:3], v30, v30, v41
	v_rcp_f32_e32 v37, v36
	s_nop 0
	v_fma_f32 v38, -v36, v37, 1.0
	v_fmac_f32_e32 v37, v38, v37
	v_div_scale_f32 v38, vcc, v41, v30, v41
	v_mul_f32_e32 v39, v38, v37
	v_fma_f32 v40, -v36, v39, v38
	v_fmac_f32_e32 v39, v40, v37
	v_fma_f32 v36, -v36, v39, v38
	v_div_fmas_f32 v36, v36, v37, v39
	v_div_fixup_f32 v30, v36, v30, v41
	v_and_b32_e32 v41, 0xffff0000, v32
	v_pk_mul_f32 v[26:27], v[30:31], v[26:27]
	v_lshlrev_b32_e32 v38, 16, v33
	v_lshlrev_b32_e32 v39, 16, v32
	v_mul_f32_e32 v31, 0xbfb8aa3b, v41
	v_mul_f32_e32 v30, 0xbfb8aa3b, v39
	v_exp_f32_e32 v32, v31
	v_mul_f32_e32 v31, 0xbfb8aa3b, v38
	v_exp_f32_e32 v30, v30
	v_exp_f32_e32 v31, v31
	v_and_b32_e32 v40, 0xffff0000, v33
	v_lshlrev_b32_e32 v37, 16, v29
	v_lshlrev_b32_e32 v36, 16, v28
	v_pk_add_f32 v[30:31], v[30:31], 1.0 op_sel_hi:[1,0]
	v_and_b32_e32 v29, 0xffff0000, v29
	v_div_scale_f32 v33, s[2:3], v31, v31, v38
	v_rcp_f32_e32 v42, v33
	v_and_b32_e32 v28, 0xffff0000, v28
	v_fma_f32 v43, -v33, v42, 1.0
	v_fmac_f32_e32 v42, v43, v42
	v_div_scale_f32 v43, vcc, v38, v31, v38
	v_mul_f32_e32 v44, v43, v42
	v_fma_f32 v45, -v33, v44, v43
	v_fmac_f32_e32 v44, v45, v42
	v_fma_f32 v33, -v33, v44, v43
	v_div_fmas_f32 v33, v33, v42, v44
	v_div_fixup_f32 v31, v33, v31, v38
	v_div_scale_f32 v33, s[2:3], v30, v30, v39
	v_rcp_f32_e32 v38, v33
	s_nop 0
	v_fma_f32 v42, -v33, v38, 1.0
	v_fmac_f32_e32 v38, v42, v38
	v_div_scale_f32 v42, vcc, v39, v30, v39
	v_mul_f32_e32 v43, v42, v38
	v_fma_f32 v44, -v33, v43, v42
	v_fmac_f32_e32 v43, v44, v38
	v_fma_f32 v33, -v33, v43, v42
	v_div_fmas_f32 v33, v33, v38, v43
	v_div_fixup_f32 v30, v33, v30, v39
	v_mul_f32_e32 v33, 0xbfb8aa3b, v40
	v_exp_f32_e32 v33, v33
	v_pk_mul_f32 v[30:31], v[30:31], v[36:37]
	v_pk_add_f32 v[32:33], v[32:33], 1.0 op_sel_hi:[1,0]
	s_nop 0
	v_div_scale_f32 v36, s[2:3], v33, v33, v40
	v_rcp_f32_e32 v37, v36
	s_nop 0
	v_fma_f32 v38, -v36, v37, 1.0
	v_fmac_f32_e32 v37, v38, v37
	v_div_scale_f32 v38, vcc, v40, v33, v40
	v_mul_f32_e32 v39, v38, v37
	v_fma_f32 v42, -v36, v39, v38
	v_fmac_f32_e32 v39, v42, v37
	v_fma_f32 v36, -v36, v39, v38
	v_div_fmas_f32 v36, v36, v37, v39
	v_div_fixup_f32 v33, v36, v33, v40
	v_div_scale_f32 v36, s[2:3], v32, v32, v41
	v_rcp_f32_e32 v37, v36
	s_nop 0
	v_fma_f32 v38, -v36, v37, 1.0
	v_fmac_f32_e32 v37, v38, v37
	v_div_scale_f32 v38, vcc, v41, v32, v41
	v_mul_f32_e32 v39, v38, v37
	v_fma_f32 v40, -v36, v39, v38
	v_fmac_f32_e32 v39, v40, v37
	v_fma_f32 v36, -v36, v39, v38
	v_div_fmas_f32 v36, v36, v37, v39
	v_div_fixup_f32 v32, v36, v32, v41
	v_pk_mul_f32 v[28:29], v[32:33], v[28:29]
	v_bfe_u32 v36, v27, 16, 1
	v_bfe_u32 v32, v29, 16, 1
	v_bfe_u32 v33, v28, 16, 1
	v_bfe_u32 v37, v26, 16, 1
	v_add3_u32 v26, v26, v37, s24
	v_add3_u32 v27, v27, v36, s24
	v_add3_u32 v28, v28, v33, s24
	v_add3_u32 v29, v29, v32, s24
	v_bfe_u32 v32, v34, 16, 1
	v_bfe_u32 v33, v35, 16, 1
	v_bfe_u32 v36, v30, 16, 1
	v_bfe_u32 v37, v31, 16, 1
	v_add3_u32 v31, v31, v37, s24
	v_add3_u32 v30, v30, v36, s24
	v_add3_u32 v33, v35, v33, s24
	v_add3_u32 v32, v34, v32, s24
	v_lshrrev_b32_e32 v32, 16, v32
	v_lshrrev_b32_e32 v33, 16, v33
	v_lshrrev_b32_e32 v30, 16, v30
	v_lshrrev_b32_e32 v31, 16, v31
	v_and_or_b32 v29, v29, s21, v31
	v_and_or_b32 v28, v28, s21, v30
	v_and_or_b32 v27, v27, s21, v33
	v_and_or_b32 v26, v26, s21, v32
	global_store_dwordx4 v[78:79], v[26:29], off offset:2048
	s_waitcnt vmcnt(9)
	v_lshlrev_b32_e32 v30, 16, v22
	v_lshlrev_b32_e32 v31, 16, v23
	v_and_b32_e32 v28, 0xffff0000, v22
	v_and_b32_e32 v29, 0xffff0000, v23
	v_lshlrev_b32_e32 v26, 16, v24
	v_and_b32_e32 v22, 0xffff0000, v24
	v_lshlrev_b32_e32 v27, 16, v25
	v_and_b32_e32 v23, 0xffff0000, v25
	v_lshlrev_b32_e32 v25, 16, v19
	v_lshlrev_b32_e32 v24, 16, v18
	v_and_b32_e32 v19, 0xffff0000, v19
	v_and_b32_e32 v18, 0xffff0000, v18
	v_pk_fma_f32 v[28:29], v[2:3], v[28:29], v[18:19] neg_lo:[1,0,0] neg_hi:[1,0,0]
	v_pk_fma_f32 v[30:31], v[2:3], v[30:31], v[24:25] neg_lo:[1,0,0] neg_hi:[1,0,0]
	v_pk_mul_f32 v[18:19], v[28:29], v[28:29]
	s_waitcnt vmcnt(8)
; __device__ __forceinline__ unsigned pk2(float lo, float hi) { return f2bf(lo) | (f2bf(hi) << 16); }
; __device__ __forceinline__ float silu(float x) { return x / (1.f + __expf(-x)); }
; __global__ void __launch_bounds__(NWAVES * 64, 2) hybrid_fwd(Args args) {
;     ...
;             for (int j = 0; j < 4; ++j) { float d[8]; float ss = 0.f;
; #pragma unroll
;                 for (int e = 0; e < 4; ++e) { const float d0 = bflo(a[j][e]) - lam * bflo(b[j][e]), d1 = bfhi(a[j][e]) - lam * bfhi(b[j][e]); d[2 * e] = d0; d[2 * e + 1] = d1; ss += d0 * d0 + d1 * d1; }
;                 ss += __shfl_xor(ss, 1); ss += __shfl_xor(ss, 2); ss += __shfl_xor(ss, 4); ss += __shfl_xor(ss, 8); ss += __shfl_xor(ss, 16);
;                 const float rstd = (1.f - LAMBDA_INIT) / sqrtf(ss * (1.f / 256.f) + RMS_EPS); v4u o;
; #pragma unroll
;                 for (int e = 0; e < 4; ++e) { const f32x4 s4 = (e >> 1) ? sl1 : sl0;
;                     o[e] = pk2(d[2 * e] * rstd * s4[(e & 1) * 2] * silu(bflo(gt[j][e])), d[2 * e + 1] * rstd * s4[(e & 1) * 2 + 1] * silu(bfhi(gt[j][e]))); }
;                 po[64 * j] = o;
	v_lshlrev_b32_e32 v24, 16, v15
	v_lshlrev_b32_e32 v25, 16, v14
	v_pk_fma_f32 v[32:33], v[30:31], v[30:31], v[18:19]
	v_mul_f32_e32 v18, 0xbfb8aa3b, v25
	v_and_b32_e32 v34, 0xffff0000, v15
	v_mul_f32_e32 v15, 0xbfb8aa3b, v24
	v_exp_f32_e32 v18, v18
	v_exp_f32_e32 v19, v15
	v_and_b32_e32 v36, 0xffff0000, v14
	v_mul_f32_e32 v14, 0xbfb8aa3b, v36
	v_exp_f32_e32 v14, v14
	v_pk_add_f32 v[18:19], v[18:19], 1.0 op_sel_hi:[1,0]
	s_nop 0
	v_div_scale_f32 v15, s[2:3], v19, v19, v24
	v_rcp_f32_e32 v35, v15
	s_nop 0
	v_fma_f32 v37, -v15, v35, 1.0
	v_fmac_f32_e32 v35, v37, v35
	v_div_scale_f32 v37, vcc, v24, v19, v24
	v_mul_f32_e32 v38, v37, v35
	v_fma_f32 v39, -v15, v38, v37
	v_fmac_f32_e32 v38, v39, v35
	v_fma_f32 v15, -v15, v38, v37
	v_div_fmas_f32 v15, v15, v35, v38
	v_div_fixup_f32 v19, v15, v19, v24
	v_div_scale_f32 v15, s[2:3], v18, v18, v25
	v_rcp_f32_e32 v24, v15
	s_nop 0
	v_fma_f32 v35, -v15, v24, 1.0
	v_fmac_f32_e32 v24, v35, v24
	v_div_scale_f32 v35, vcc, v25, v18, v25
	v_mul_f32_e32 v37, v35, v24
	v_fma_f32 v38, -v15, v37, v35
	v_fmac_f32_e32 v37, v38, v24
	v_fma_f32 v15, -v15, v37, v35
	v_div_fmas_f32 v15, v15, v24, v37
	v_div_fixup_f32 v18, v15, v18, v25
	v_mul_f32_e32 v15, 0xbfb8aa3b, v34
	v_exp_f32_e32 v15, v15
	s_nop 0
	v_pk_add_f32 v[14:15], v[14:15], 1.0 op_sel_hi:[1,0]
	s_nop 0
	v_div_scale_f32 v24, s[2:3], v15, v15, v34
	v_rcp_f32_e32 v25, v24
	s_nop 0
	v_fma_f32 v35, -v24, v25, 1.0
	v_fmac_f32_e32 v25, v35, v25
	v_div_scale_f32 v35, vcc, v34, v15, v34
	v_mul_f32_e32 v37, v35, v25
	v_fma_f32 v38, -v24, v37, v35
	v_fmac_f32_e32 v37, v38, v25
	v_fma_f32 v24, -v24, v37, v35
	v_div_fmas_f32 v24, v24, v25, v37
	v_div_fixup_f32 v35, v24, v15, v34
	v_div_scale_f32 v15, s[2:3], v14, v14, v36
	v_rcp_f32_e32 v24, v15
	s_nop 0
	v_fma_f32 v25, -v15, v24, 1.0
	v_fmac_f32_e32 v24, v25, v24
	v_div_scale_f32 v25, vcc, v36, v14, v36
	v_mul_f32_e32 v34, v25, v24
	v_fma_f32 v37, -v15, v34, v25
	v_fmac_f32_e32 v34, v37, v24
	v_fma_f32 v15, -v15, v34, v25
	v_div_fmas_f32 v15, v15, v24, v34
	v_div_fixup_f32 v34, v15, v14, v36
	v_lshlrev_b32_e32 v15, 16, v21
	v_lshlrev_b32_e32 v14, 16, v20
	v_pk_fma_f32 v[24:25], v[2:3], v[26:27], v[14:15] neg_lo:[1,0,0] neg_hi:[1,0,0]
	v_and_b32_e32 v15, 0xffff0000, v21
	v_and_b32_e32 v14, 0xffff0000, v20
	v_pk_fma_f32 v[14:15], v[2:3], v[22:23], v[14:15] neg_lo:[1,0,0] neg_hi:[1,0,0]
	v_add_f32_e32 v22, v32, v33
	v_pk_mul_f32 v[20:21], v[14:15], v[14:15]
	s_nop 0
	v_pk_fma_f32 v[20:21], v[24:25], v[24:25], v[20:21]
	s_nop 0
	v_add_f32_e32 v20, v22, v20
	v_add_f32_e32 v20, v20, v21
	ds_bpermute_b32 v21, v88, v20
	s_waitcnt lgkmcnt(0)
	v_add_f32_e32 v20, v20, v21
	ds_bpermute_b32 v21, v89, v20
	s_waitcnt lgkmcnt(0)
	v_add_f32_e32 v20, v20, v21
	ds_bpermute_b32 v21, v90, v20
	s_waitcnt lgkmcnt(0)
	v_add_f32_e32 v20, v20, v21
	ds_bpermute_b32 v21, v91, v20
	s_waitcnt lgkmcnt(0)
	v_add_f32_e32 v20, v20, v21
	ds_bpermute_b32 v21, v92, v20
	s_waitcnt lgkmcnt(0)
	v_add_f32_e32 v20, v20, v21
	v_fmamk_f32 v20, v20, 0x3b800000, v93
	v_cmp_gt_f32_e32 vcc, s22, v20
	v_mul_f32_e32 v21, 0x4f800000, v20
	s_nop 0
	v_cndmask_b32_e32 v20, v20, v21, vcc
	v_sqrt_f32_e32 v21, v20
	s_nop 0
	v_add_u32_e32 v22, -1, v21
	v_fma_f32 v23, -v22, v21, v20
	v_cmp_ge_f32_e64 s[2:3], 0, v23
	v_add_u32_e32 v23, 1, v21
	s_nop 0
	v_cndmask_b32_e64 v22, v21, v22, s[2:3]
	v_fma_f32 v21, -v23, v21, v20
	v_cmp_lt_f32_e64 s[2:3], 0, v21
	s_nop 1
	v_cndmask_b32_e64 v21, v22, v23, s[2:3]
	v_mul_f32_e32 v22, 0x37800000, v21
	v_cndmask_b32_e32 v21, v21, v22, vcc
	v_cmp_class_f32_e32 vcc, v20, v94
	s_nop 1
	v_cndmask_b32_e32 v20, v21, v20, vcc
	v_div_scale_f32 v21, s[2:3], v20, v20, s23
	v_rcp_f32_e32 v22, v21
	s_nop 0
	v_fma_f32 v23, -v21, v22, 1.0
	v_fmac_f32_e32 v22, v23, v22
	v_div_scale_f32 v23, vcc, s23, v20, s23
	v_mul_f32_e32 v26, v23, v22
	v_fma_f32 v27, -v21, v26, v23
	v_fmac_f32_e32 v26, v27, v22
	v_fma_f32 v21, -v21, v26, v23
	v_div_fmas_f32 v21, v21, v22, v26
	v_div_fixup_f32 v22, v21, v20, s23
	v_pk_mul_f32 v[20:21], v[22:23], v[30:31] op_sel_hi:[0,1]
	v_pk_mul_f32 v[20:21], v[0:1], v[20:21]
	v_and_b32_e32 v30, 0xffff0000, v16
	v_pk_mul_f32 v[18:19], v[20:21], v[18:19]
	v_pk_mul_f32 v[20:21], v[22:23], v[28:29] op_sel_hi:[0,1]
	v_lshlrev_b32_e32 v23, 16, v17
	v_lshlrev_b32_e32 v28, 16, v16
	v_mul_f32_e32 v26, 0xbfb8aa3b, v28
	v_and_b32_e32 v29, 0xffff0000, v17
	v_mul_f32_e32 v17, 0xbfb8aa3b, v23
	v_exp_f32_e32 v26, v26
	v_exp_f32_e32 v27, v17
	v_pk_mul_f32 v[20:21], v[82:83], v[20:21]
	v_pk_mul_f32 v[24:25], v[22:23], v[24:25] op_sel_hi:[0,1]
	v_pk_mul_f32 v[20:21], v[20:21], v[34:35]
	v_pk_add_f32 v[26:27], v[26:27], 1.0 op_sel_hi:[1,0]
	v_mul_f32_e32 v16, 0xbfb8aa3b, v30
	v_div_scale_f32 v17, s[2:3], v27, v27, v23
	v_rcp_f32_e32 v31, v17
	v_exp_f32_e32 v16, v16
	v_pk_mul_f32 v[24:25], v[4:5], v[24:25]
	v_fma_f32 v32, -v17, v31, 1.0
	v_fmac_f32_e32 v31, v32, v31
	v_div_scale_f32 v32, vcc, v23, v27, v23
	v_mul_f32_e32 v33, v32, v31
	v_fma_f32 v34, -v17, v33, v32
	v_fmac_f32_e32 v33, v34, v31
	v_fma_f32 v17, -v17, v33, v32
	v_div_fmas_f32 v17, v17, v31, v33
	v_div_fixup_f32 v27, v17, v27, v23
	v_div_scale_f32 v17, s[2:3], v26, v26, v28
	v_rcp_f32_e32 v23, v17
	s_nop 0
	v_fma_f32 v31, -v17, v23, 1.0
	v_fmac_f32_e32 v23, v31, v23
	v_div_scale_f32 v31, vcc, v28, v26, v28
	v_mul_f32_e32 v32, v31, v23
	v_fma_f32 v33, -v17, v32, v31
	v_fmac_f32_e32 v32, v33, v23
	v_fma_f32 v17, -v17, v32, v31
	v_div_fmas_f32 v17, v17, v23, v32
	v_div_fixup_f32 v26, v17, v26, v28
	v_mul_f32_e32 v17, 0xbfb8aa3b, v29
	v_exp_f32_e32 v17, v17
	v_pk_mul_f32 v[14:15], v[22:23], v[14:15] op_sel_hi:[0,1]
	v_pk_mul_f32 v[24:25], v[24:25], v[26:27]
	v_pk_mul_f32 v[14:15], v[84:85], v[14:15]
; __device__ __forceinline__ unsigned pk2(float lo, float hi) { return f2bf(lo) | (f2bf(hi) << 16); }
; __device__ __forceinline__ float silu(float x) { return x / (1.f + __expf(-x)); }
; __global__ void __launch_bounds__(NWAVES * 64, 2) hybrid_fwd(Args args) {
;     ...
;                 for (int e = 0; e < 4; ++e) { const f32x4 s4 = (e >> 1) ? sl1 : sl0;
;                     o[e] = pk2(d[2 * e] * rstd * s4[(e & 1) * 2] * silu(bflo(gt[j][e])), d[2 * e + 1] * rstd * s4[(e & 1) * 2 + 1] * silu(bfhi(gt[j][e]))); }
;                 po[64 * j] = o;
;                 v4u o2;
; #pragma unroll
;                 for (int e = 0; e < 4; ++e) o2[e] = pk2(bflo(ab[j][e]) * silu(bflo(gm[j][e])), bfhi(ab[j][e]) * silu(bfhi(gm[j][e])));
;                 po[256 + 64 * j] = o2; }
;         }
	v_pk_add_f32 v[16:17], v[16:17], 1.0 op_sel_hi:[1,0]
	s_nop 0
	v_div_scale_f32 v22, s[2:3], v17, v17, v29
	v_rcp_f32_e32 v23, v22
	s_nop 0
	v_fma_f32 v26, -v22, v23, 1.0
	v_fmac_f32_e32 v23, v26, v23
	v_div_scale_f32 v26, vcc, v29, v17, v29
	v_mul_f32_e32 v27, v26, v23
	v_fma_f32 v28, -v22, v27, v26
	v_fmac_f32_e32 v27, v28, v23
	v_fma_f32 v22, -v22, v27, v26
	v_div_fmas_f32 v22, v22, v23, v27
	v_div_fixup_f32 v17, v22, v17, v29
	v_div_scale_f32 v22, s[2:3], v16, v16, v30
	v_rcp_f32_e32 v23, v22
	s_nop 0
	v_fma_f32 v26, -v22, v23, 1.0
	v_fmac_f32_e32 v23, v26, v23
	v_div_scale_f32 v26, vcc, v30, v16, v30
	v_mul_f32_e32 v27, v26, v23
	v_fma_f32 v28, -v22, v27, v26
	v_fmac_f32_e32 v27, v28, v23
	v_fma_f32 v22, -v22, v27, v26
	v_div_fmas_f32 v22, v22, v23, v27
	v_div_fixup_f32 v16, v22, v16, v30
	v_pk_mul_f32 v[14:15], v[14:15], v[16:17]
	v_bfe_u32 v22, v21, 16, 1
	v_bfe_u32 v16, v15, 16, 1
	v_bfe_u32 v17, v14, 16, 1
	v_bfe_u32 v23, v20, 16, 1
	v_add3_u32 v20, v20, v23, s24
	v_add3_u32 v21, v21, v22, s24
	v_add3_u32 v14, v14, v17, s24
	v_add3_u32 v15, v15, v16, s24
	v_bfe_u32 v16, v18, 16, 1
	v_bfe_u32 v17, v19, 16, 1
	v_bfe_u32 v22, v24, 16, 1
	v_bfe_u32 v23, v25, 16, 1
	v_add3_u32 v23, v25, v23, s24
	v_add3_u32 v22, v24, v22, s24
	v_add3_u32 v17, v19, v17, s24
	v_add3_u32 v16, v18, v16, s24
	v_lshrrev_b32_e32 v18, 16, v16
	v_lshrrev_b32_e32 v19, 16, v17
	v_lshrrev_b32_e32 v16, 16, v22
	v_lshrrev_b32_e32 v17, 16, v23
	v_and_or_b32 v17, v15, s21, v17
	v_and_or_b32 v16, v14, s21, v16
	v_and_or_b32 v15, v21, s21, v19
	v_and_or_b32 v14, v20, s21, v18
	global_store_dwordx4 v[80:81], v[14:17], off offset:3072
	s_waitcnt vmcnt(7)
	v_lshlrev_b32_e32 v18, 16, v10
	v_and_b32_e32 v20, 0xffff0000, v10
	v_lshlrev_b32_e32 v17, 16, v11
	v_mul_f32_e32 v14, 0xbfb8aa3b, v18
	v_mul_f32_e32 v15, 0xbfb8aa3b, v17
	v_exp_f32_e32 v14, v14
	v_exp_f32_e32 v15, v15
	v_mul_f32_e32 v10, 0xbfb8aa3b, v20
	v_and_b32_e32 v19, 0xffff0000, v11
	v_exp_f32_e32 v16, v10
	v_pk_add_f32 v[14:15], v[14:15], 1.0 op_sel_hi:[1,0]
	v_lshlrev_b32_e32 v11, 16, v7
	v_div_scale_f32 v21, s[2:3], v15, v15, v17
	v_rcp_f32_e32 v22, v21
	v_lshlrev_b32_e32 v10, 16, v6
	v_and_b32_e32 v7, 0xffff0000, v7
	v_and_b32_e32 v6, 0xffff0000, v6
	v_fma_f32 v23, -v21, v22, 1.0
	v_fmac_f32_e32 v22, v23, v22
	v_div_scale_f32 v23, vcc, v17, v15, v17
	v_mul_f32_e32 v24, v23, v22
	v_fma_f32 v25, -v21, v24, v23
	v_fmac_f32_e32 v24, v25, v22
	v_fma_f32 v21, -v21, v24, v23
	v_div_fmas_f32 v21, v21, v22, v24
	v_div_fixup_f32 v15, v21, v15, v17
	v_div_scale_f32 v17, s[2:3], v14, v14, v18
	v_rcp_f32_e32 v21, v17
	s_nop 0
	v_fma_f32 v22, -v17, v21, 1.0
	v_fmac_f32_e32 v21, v22, v21
	v_div_scale_f32 v22, vcc, v18, v14, v18
	v_mul_f32_e32 v23, v22, v21
	v_fma_f32 v24, -v17, v23, v22
	v_fmac_f32_e32 v23, v24, v21
	v_fma_f32 v17, -v17, v23, v22
	v_div_fmas_f32 v17, v17, v21, v23
	v_div_fixup_f32 v14, v17, v14, v18
	v_pk_mul_f32 v[10:11], v[14:15], v[10:11]
	v_mul_f32_e32 v14, 0xbfb8aa3b, v19
	v_exp_f32_e32 v17, v14
	s_nop 0
	v_pk_add_f32 v[14:15], v[16:17], 1.0 op_sel_hi:[1,0]
	s_nop 0
	v_div_scale_f32 v16, s[2:3], v15, v15, v19
	v_rcp_f32_e32 v17, v16
	s_nop 0
	v_fma_f32 v18, -v16, v17, 1.0
	v_fmac_f32_e32 v17, v18, v17
	v_div_scale_f32 v18, vcc, v19, v15, v19
	v_mul_f32_e32 v21, v18, v17
	v_fma_f32 v22, -v16, v21, v18
	v_fmac_f32_e32 v21, v22, v17
	v_fma_f32 v16, -v16, v21, v18
	v_div_fmas_f32 v16, v16, v17, v21
	v_div_fixup_f32 v15, v16, v15, v19
	v_div_scale_f32 v16, s[2:3], v14, v14, v20
	v_rcp_f32_e32 v17, v16
	s_nop 0
	v_fma_f32 v18, -v16, v17, 1.0
	v_fmac_f32_e32 v17, v18, v17
	v_div_scale_f32 v18, vcc, v20, v14, v20
	v_mul_f32_e32 v19, v18, v17
	v_fma_f32 v21, -v16, v19, v18
	v_fmac_f32_e32 v19, v21, v17
	v_fma_f32 v16, -v16, v19, v18
	v_div_fmas_f32 v16, v16, v17, v19
	v_div_fixup_f32 v14, v16, v14, v20
	v_pk_mul_f32 v[6:7], v[14:15], v[6:7]
	v_lshlrev_b32_e32 v15, 16, v13
	v_lshlrev_b32_e32 v20, 16, v12
	v_mul_f32_e32 v14, 0xbfb8aa3b, v20
	v_mul_f32_e32 v19, 0xbfb8aa3b, v15
	v_exp_f32_e32 v18, v14
	v_exp_f32_e32 v19, v19
	v_and_b32_e32 v17, 0xffff0000, v13
	v_and_b32_e32 v16, 0xffff0000, v12
	v_mul_f32_e32 v12, 0xbfb8aa3b, v16
	v_pk_add_f32 v[18:19], v[18:19], 1.0 op_sel_hi:[1,0]
	v_exp_f32_e32 v14, v12
	v_div_scale_f32 v21, s[2:3], v19, v19, v15
	v_rcp_f32_e32 v22, v21
	v_lshlrev_b32_e32 v13, 16, v9
	v_lshlrev_b32_e32 v12, 16, v8
	v_and_b32_e32 v9, 0xffff0000, v9
	v_fma_f32 v23, -v21, v22, 1.0
	v_fmac_f32_e32 v22, v23, v22
	v_div_scale_f32 v23, vcc, v15, v19, v15
	v_mul_f32_e32 v24, v23, v22
	v_fma_f32 v25, -v21, v24, v23
	v_fmac_f32_e32 v24, v25, v22
	v_fma_f32 v21, -v21, v24, v23
	v_div_fmas_f32 v21, v21, v22, v24
	v_div_fixup_f32 v19, v21, v19, v15
	v_div_scale_f32 v15, s[2:3], v18, v18, v20
	v_rcp_f32_e32 v21, v15
	v_and_b32_e32 v8, 0xffff0000, v8
	v_fma_f32 v22, -v15, v21, 1.0
	v_fmac_f32_e32 v21, v22, v21
	v_div_scale_f32 v22, vcc, v20, v18, v20
	v_mul_f32_e32 v23, v22, v21
	v_fma_f32 v24, -v15, v23, v22
	v_fmac_f32_e32 v23, v24, v21
	v_fma_f32 v15, -v15, v23, v22
	v_div_fmas_f32 v15, v15, v21, v23
	v_div_fixup_f32 v18, v15, v18, v20
	v_mul_f32_e32 v15, 0xbfb8aa3b, v17
	v_exp_f32_e32 v15, v15
	v_pk_mul_f32 v[12:13], v[18:19], v[12:13]
	v_pk_add_f32 v[14:15], v[14:15], 1.0 op_sel_hi:[1,0]
	s_nop 0
	v_div_scale_f32 v18, s[2:3], v15, v15, v17
	v_rcp_f32_e32 v19, v18
	s_nop 0
	v_fma_f32 v20, -v18, v19, 1.0
	v_fmac_f32_e32 v19, v20, v19
	v_div_scale_f32 v20, vcc, v17, v15, v17
	v_mul_f32_e32 v21, v20, v19
	v_fma_f32 v22, -v18, v21, v20
	v_fmac_f32_e32 v21, v22, v19
	v_fma_f32 v18, -v18, v21, v20
	v_div_fmas_f32 v18, v18, v19, v21
	v_div_fixup_f32 v15, v18, v15, v17
	v_div_scale_f32 v17, s[2:3], v14, v14, v16
	v_rcp_f32_e32 v18, v17
	s_nop 0
	v_fma_f32 v19, -v17, v18, 1.0
	v_fmac_f32_e32 v18, v19, v18
	v_div_scale_f32 v19, vcc, v16, v14, v16
	v_mul_f32_e32 v20, v19, v18
	v_fma_f32 v21, -v17, v20, v19
	v_fmac_f32_e32 v20, v21, v18
	v_fma_f32 v17, -v17, v20, v19
	v_div_fmas_f32 v17, v17, v18, v20
	v_div_fixup_f32 v14, v17, v14, v16
	v_pk_mul_f32 v[8:9], v[14:15], v[8:9]
	v_bfe_u32 v16, v7, 16, 1
	v_bfe_u32 v14, v9, 16, 1
	v_bfe_u32 v15, v8, 16, 1
	v_bfe_u32 v17, v6, 16, 1
	v_add3_u32 v6, v6, v17, s24
	v_add3_u32 v7, v7, v16, s24
	v_add3_u32 v8, v8, v15, s24
	v_add3_u32 v9, v9, v14, s24
	v_bfe_u32 v14, v10, 16, 1
	v_bfe_u32 v15, v11, 16, 1
	v_bfe_u32 v16, v12, 16, 1
	v_bfe_u32 v17, v13, 16, 1
	v_add3_u32 v13, v13, v17, s24
	v_add3_u32 v12, v12, v16, s24
	v_add3_u32 v11, v11, v15, s24
	v_add3_u32 v10, v10, v14, s24
	v_lshrrev_b32_e32 v10, 16, v10
	v_lshrrev_b32_e32 v11, 16, v11
	v_lshrrev_b32_e32 v12, 16, v12
	v_lshrrev_b32_e32 v13, 16, v13
	v_and_or_b32 v9, v9, s21, v13
	v_and_or_b32 v8, v8, s21, v12
	v_and_or_b32 v7, v7, s21, v11
	v_and_or_b32 v6, v6, s21, v10
	global_store_dwordx4 v[78:79], v[6:9], off offset:3072
	s_cbranch_scc1 .LBB0_847
